# one static s_setprio 1 for waves 4-7 at kernel entry, all per-segment s_setprio flips removed
# speedup vs baseline: 1.0015x; 1.0015x over previous
; #define LAS __attribute__((address_space(3)))
; __device__ __forceinline__ void phase_prologue(const Ctx& C) {
;     ...
;     if ((int)blockIdx.x < 48) {
;         LAS float* sc = (LAS float*)C.lds;
;         LAS float* red = (LAS float*)(C.lds + 32768);
;         const float* cin = C.in[1];
;         for (int i = tid; i < BATCH * DM; i += 512) { const float v = cin[i]; sc[i] = v / (1.f + __expf(-v)); }
; __global__ void __launch_bounds__(NWAVES * 64, 2) fwd_megakernel(Args args) {
;     ...
;     for (int i = 0; i < 14; ++i) C.in[i] = args.in[i];
;     C.out = args.out; C.ws = args.ws;
;     C.lds = (LAS unsigned char*)lds;
;     C.tid = threadIdx.x; C.lane = C.tid & 63; C.wave = __builtin_amdgcn_readfirstlane(C.tid >> 6);
;     C.G = gridDim.x; { const int bx = blockIdx.x; C.vcu = (C.G % 8 == 0) ? (bx % 8) * (C.G / 8) + bx / 8 : bx; }
;     { volatile LAS unsigned* misc = (volatile LAS unsigned*)(C.lds + BAR_LDS_OFF); if (C.tid < 2) misc[C.tid] = 0u; }
.LBB0_7:
	s_or_b64 exec, exec, s[2:3]
	s_load_dwordx16 s[64:79], s[0:1], 0x0
	s_lshr_b32 s0, s10, 6
	s_cmp_lt_u32 s0, 4
	s_cbranch_scc1 .Lprio_done
	s_setprio 1
.Lprio_done:
	v_and_b32_e32 v162, 63, v163
	v_mov_b32_e32 v44, v162
	v_mov_b32_e32 v34, v163
	s_waitcnt lgkmcnt(0)
	v_writelane_b32 v254, s64, 4
	s_mov_b64 s[4:5], s[62:63]
	s_nop 0
	v_writelane_b32 v254, s65, 5
	v_writelane_b32 v254, s66, 6
	v_writelane_b32 v254, s67, 7
	v_writelane_b32 v254, s68, 8
	v_writelane_b32 v254, s69, 9
	v_writelane_b32 v254, s70, 10
	v_writelane_b32 v254, s71, 11
	v_writelane_b32 v254, s72, 12
	v_writelane_b32 v254, s73, 13
	v_writelane_b32 v254, s74, 14
	v_writelane_b32 v254, s75, 15
	v_writelane_b32 v254, s76, 16
	v_writelane_b32 v254, s77, 17
	v_writelane_b32 v254, s78, 18
	v_writelane_b32 v254, s79, 19
	v_writelane_b32 v254, s0, 20
	s_mov_b64 s[0:1], s[60:61]
	v_readlane_b32 s2, v254, 0
	s_cmp_gt_i32 s2, 47
	s_cbranch_scc1 .LBB0_14
	s_movk_i32 s0, 0x2000
	v_cmp_gt_i32_e32 vcc, s0, v34
	s_and_saveexec_b64 s[0:1], vcc
	s_cbranch_execz .LBB0_11
	v_readlane_b32 s64, v254, 4
	v_readlane_b32 s66, v254, 6
	v_readlane_b32 s67, v254, 7
	v_ashrrev_i32_e32 v35, 31, v34
	v_mov_b32_e32 v2, s66
	v_mov_b32_e32 v3, s67
	v_add_u32_e32 v1, 0xfffffe00, v34
	v_lshl_add_u32 v4, v34, 2, 0
	v_lshl_add_u64 v[2:3], v[34:35], 2, v[2:3]
	s_mov_b64 s[2:3], 0
	s_mov_b64 s[10:11], 0x800
	s_movk_i32 s12, 0x1dff
	v_readlane_b32 s65, v254, 5
	v_readlane_b32 s68, v254, 8
	v_readlane_b32 s69, v254, 9
	v_readlane_b32 s70, v254, 10
	v_readlane_b32 s71, v254, 11
	v_readlane_b32 s72, v254, 12
	v_readlane_b32 s73, v254, 13
	v_readlane_b32 s74, v254, 14
	v_readlane_b32 s75, v254, 15
	v_readlane_b32 s76, v254, 16
	v_readlane_b32 s77, v254, 17
	v_readlane_b32 s78, v254, 18
	v_readlane_b32 s79, v254, 19

; #define PG8_STAGE(bufoff, gbase, voff) do { _Pragma("unroll") for (int _i = 0; _i < 2; ++_i) \
;         __builtin_amdgcn_global_load_lds((const unsigned*)((const char*)(gbase) + (voff)[_i]), (PG8_LAS unsigned*)(lds + (bufoff) + ldsw + _i * 8192), 16, 0, 0); } while (0)
; #define PG8_LDA(dst, b, h) do { _Pragma("unroll") for (int m = 0; m < 4; ++m) _Pragma("unroll") for (int k = 0; k < 2; ++k) dst[m][k] = *(const PG8_LAS bf16x8*)(lds + PG8_SA(b, h) + aoff + m * 2048 + k * 1024); } while (0)
; #define PG8_LDB(dst, b, h) do { _Pragma("unroll") for (int n = 0; n < 2; ++n) _Pragma("unroll") for (int k = 0; k < 2; ++k) dst[n][k] = *(const PG8_LAS bf16x8*)(lds + PG8_SB(b, h) + boff + n * 2048 + k * 1024); } while (0)
; #define PG8_MMA(ai, bj, At, Bt) do { __builtin_amdgcn_s_setprio(1); _Pragma("unroll") for (int m = 0; m < 4; ++m) _Pragma("unroll") for (int n = 0; n < 2; ++n) _Pragma("unroll") for (int k = 0; k < 2; ++k) \
;         acc[ai][bj][m][n] = __builtin_amdgcn_mfma_f32_16x16x32_bf16(Bt[n][k], At[m][k], acc[ai][bj][m][n], 0, 0, 0); __builtin_amdgcn_s_setprio(0); } while (0)
; #define PG8_WAIT_V(n) asm volatile("s_waitcnt vmcnt(" #n ")" ::: "memory")
; #define PG8_WAIT_L(n) asm volatile("s_waitcnt lgkmcnt(" #n ")" ::: "memory")
; #define PG8_BAR __builtin_amdgcn_s_barrier()
; #define PG8_SCHED __builtin_amdgcn_sched_barrier(0)
; template <class Epi, class Sched, bool ALIGN_EPI = false, bool SP2 = false, bool MID = false>
; __device__ __forceinline__ void gemm_phase(PG8_LAS unsigned char* lds, const Gemm g, const Sched& S, const Epi& E, const PG8_LAS float* mid = nullptr) {
;     ...
;             if constexpr (SP2) {
;             PG8_LDB(B0, 0, 0); PG8_LDB(B1, 0, 1); PG8_SCHED; PG8_LDA(At, 0, 0); PG8_STAGE(PG8_SA(1, 1), a1 + hstepA, voffA);
;             PG8_WAIT_V(8); PG8_WAIT_L(0); PG8_BAR; PG8_MMA(0, 0, At, B0); PG8_MMA(0, 1, At, B1); PG8_BAR; PG8_SCHED;
;             PG8_LDA(At, 0, 1); PG8_STAGE(PG8_SB(0, 0), b2, voffB); PG8_STAGE(PG8_SB(0, 1), b2 + hstepB, voffB); PG8_STAGE(PG8_SA(0, 0), a2, voffA);
.LBB0_192:
	s_add_u32 s3, s12, 0xfffc0080
	s_addc_u32 s48, s13, -1
	s_add_i32 s66, 0, 0x10000
	s_cmp_eq_u32 s65, 12
	s_cselect_b32 s51, s41, s48
	s_cselect_b32 s50, s61, s3
	v_add_u32_e32 v140, s66, v146
	s_cselect_b32 s49, s39, s64
	s_cselect_b32 s48, s62, s63
	s_add_i32 s3, 0, 0x14000
	ds_read_b128 v[142:145], v140
	ds_read_b128 v[150:153], v140 offset:1024
	ds_read_b128 v[154:157], v140 offset:2048
	ds_read_b128 v[158:161], v140 offset:3072
	v_add_u32_e32 v140, s3, v146
	ds_read_b128 v[174:177], v140
	ds_read_b128 v[178:181], v140 offset:1024
	ds_read_b128 v[182:185], v140 offset:2048
	ds_read_b128 v[186:189], v140 offset:3072
	v_lshl_add_u64 v[236:237], s[12:13], 0, v[136:137]
	s_add_i32 m0, s43, 0xc000
	ds_read_b128 v[190:193], v148
	ds_read_b128 v[194:197], v148 offset:1024
	ds_read_b128 v[198:201], v148 offset:2048
	ds_read_b128 v[202:205], v148 offset:3072
	ds_read_b128 v[220:223], v148 offset:4096
	ds_read_b128 v[224:227], v148 offset:5120
	ds_read_b128 v[228:231], v148 offset:6144
	ds_read_b128 v[232:235], v148 offset:7168
	global_load_lds_dwordx4 v[236:237], off
	v_lshl_add_u64 v[236:237], s[12:13], 0, v[138:139]
	s_add_i32 m0, s43, 0xe000
	s_nop 0
	global_load_lds_dwordx4 v[236:237], off
	s_waitcnt vmcnt(8)
	s_waitcnt lgkmcnt(0)
	s_barrier
	s_waitcnt lgkmcnt(0)
	v_mfma_f32_16x16x32_bf16 v[126:129], v[142:145], v[190:193], v[126:129]
	v_mfma_f32_16x16x32_bf16 v[122:125], v[154:157], v[190:193], v[122:125]
	v_mfma_f32_16x16x32_bf16 v[118:121], v[142:145], v[198:201], v[118:121]
	v_mfma_f32_16x16x32_bf16 v[110:113], v[154:157], v[198:201], v[110:113]
	v_mfma_f32_16x16x32_bf16 v[102:105], v[142:145], v[220:223], v[102:105]
	v_mfma_f32_16x16x32_bf16 v[94:97], v[154:157], v[220:223], v[94:97]
	v_mfma_f32_16x16x32_bf16 v[86:89], v[142:145], v[228:231], v[86:89]
	v_mfma_f32_16x16x32_bf16 v[76:79], v[154:157], v[228:231], v[76:79]
	v_mfma_f32_16x16x32_bf16 v[126:129], v[150:153], v[194:197], v[126:129]
	v_mfma_f32_16x16x32_bf16 v[122:125], v[158:161], v[194:197], v[122:125]
	v_mfma_f32_16x16x32_bf16 v[118:121], v[150:153], v[202:205], v[118:121]
	v_mfma_f32_16x16x32_bf16 v[110:113], v[158:161], v[202:205], v[110:113]
	v_mfma_f32_16x16x32_bf16 v[102:105], v[150:153], v[224:227], v[102:105]
	v_mfma_f32_16x16x32_bf16 v[94:97], v[158:161], v[224:227], v[94:97]
	v_mfma_f32_16x16x32_bf16 v[86:89], v[150:153], v[232:235], v[86:89]
	v_mfma_f32_16x16x32_bf16 v[76:79], v[158:161], v[232:235], v[76:79]
	v_mfma_f32_16x16x32_bf16 v[114:117], v[174:177], v[190:193], v[114:117]
	v_mfma_f32_16x16x32_bf16 v[106:109], v[182:185], v[190:193], v[106:109]
	v_mfma_f32_16x16x32_bf16 v[98:101], v[174:177], v[198:201], v[98:101]
	v_mfma_f32_16x16x32_bf16 v[90:93], v[182:185], v[198:201], v[90:93]
	v_mfma_f32_16x16x32_bf16 v[82:85], v[174:177], v[220:223], v[82:85]
	v_mfma_f32_16x16x32_bf16 v[72:75], v[182:185], v[220:223], v[72:75]
	v_mfma_f32_16x16x32_bf16 v[68:71], v[174:177], v[228:231], v[68:71]
	v_mfma_f32_16x16x32_bf16 v[64:67], v[182:185], v[228:231], v[64:67]
	v_mfma_f32_16x16x32_bf16 v[114:117], v[178:181], v[194:197], v[114:117]
	v_mfma_f32_16x16x32_bf16 v[106:109], v[186:189], v[194:197], v[106:109]
	v_mfma_f32_16x16x32_bf16 v[98:101], v[178:181], v[202:205], v[98:101]
	v_mfma_f32_16x16x32_bf16 v[90:93], v[186:189], v[202:205], v[90:93]
	v_mfma_f32_16x16x32_bf16 v[82:85], v[178:181], v[224:227], v[82:85]
	v_mfma_f32_16x16x32_bf16 v[72:75], v[186:189], v[224:227], v[72:75]
	v_mfma_f32_16x16x32_bf16 v[68:71], v[178:181], v[232:235], v[68:71]
	v_mfma_f32_16x16x32_bf16 v[64:67], v[186:189], v[232:235], v[64:67]
	s_barrier
	s_add_i32 s66, s66, s52
	v_lshl_add_u64 v[236:237], s[48:49], 0, v[80:81]
	s_mov_b32 m0, s66
	ds_read_b128 v[190:193], v148 offset:16384
	ds_read_b128 v[194:197], v148 offset:17408
	ds_read_b128 v[198:201], v148 offset:18432
	ds_read_b128 v[202:205], v148 offset:19456
	ds_read_b128 v[220:223], v148 offset:20480
	ds_read_b128 v[224:227], v148 offset:21504
	ds_read_b128 v[228:231], v148 offset:22528
	ds_read_b128 v[232:235], v148 offset:23552
	global_load_lds_dwordx4 v[236:237], off
	s_add_i32 m0, s66, 0x2000
	s_add_u32 s66, s48, 0x40000
	v_lshl_add_u64 v[238:239], s[48:49], 0, v[130:131]
	s_addc_u32 s67, s49, 0
	s_add_i32 s3, s3, s52
	global_load_lds_dwordx4 v[238:239], off
	v_lshl_add_u64 v[240:241], s[66:67], 0, v[80:81]
	s_mov_b32 m0, s3
	v_lshl_add_u64 v[242:243], s[50:51], 0, v[132:133]
	global_load_lds_dwordx4 v[240:241], off
	v_lshl_add_u64 v[240:241], s[66:67], 0, v[130:131]
	s_add_i32 m0, s3, 0x2000
	s_nop 0
	global_load_lds_dwordx4 v[240:241], off
	v_lshl_add_u64 v[240:241], s[50:51], 0, v[134:135]
	s_mov_b32 m0, s43
	s_nop 0
	global_load_lds_dwordx4 v[240:241], off
	s_mov_b32 m0, s54
	s_nop 0
	global_load_lds_dwordx4 v[242:243], off
	s_waitcnt vmcnt(8)
	s_waitcnt lgkmcnt(0)
	s_barrier
; #define PG8_STAGE(bufoff, gbase, voff) do { _Pragma("unroll") for (int _i = 0; _i < 2; ++_i) \
;         __builtin_amdgcn_global_load_lds((const unsigned*)((const char*)(gbase) + (voff)[_i]), (PG8_LAS unsigned*)(lds + (bufoff) + ldsw + _i * 8192), 16, 0, 0); } while (0)
; #define PG8_LDA(dst, b, h) do { _Pragma("unroll") for (int m = 0; m < 4; ++m) _Pragma("unroll") for (int k = 0; k < 2; ++k) dst[m][k] = *(const PG8_LAS bf16x8*)(lds + PG8_SA(b, h) + aoff + m * 2048 + k * 1024); } while (0)
; #define PG8_LDB(dst, b, h) do { _Pragma("unroll") for (int n = 0; n < 2; ++n) _Pragma("unroll") for (int k = 0; k < 2; ++k) dst[n][k] = *(const PG8_LAS bf16x8*)(lds + PG8_SB(b, h) + boff + n * 2048 + k * 1024); } while (0)
; #define PG8_MMA(ai, bj, At, Bt) do { __builtin_amdgcn_s_setprio(1); _Pragma("unroll") for (int m = 0; m < 4; ++m) _Pragma("unroll") for (int n = 0; n < 2; ++n) _Pragma("unroll") for (int k = 0; k < 2; ++k) \
;         acc[ai][bj][m][n] = __builtin_amdgcn_mfma_f32_16x16x32_bf16(Bt[n][k], At[m][k], acc[ai][bj][m][n], 0, 0, 0); __builtin_amdgcn_s_setprio(0); } while (0)
; #define PG8_WAIT_V(n) asm volatile("s_waitcnt vmcnt(" #n ")" ::: "memory")
; #define PG8_WAIT_L(n) asm volatile("s_waitcnt lgkmcnt(" #n ")" ::: "memory")
; #define PG8_BAR __builtin_amdgcn_s_barrier()
; #define PG8_SCHED __builtin_amdgcn_sched_barrier(0)
; template <class Epi, class Sched, bool ALIGN_EPI = false, bool SP2 = false, bool MID = false>
; __device__ __forceinline__ void gemm_phase(PG8_LAS unsigned char* lds, const Gemm g, const Sched& S, const Epi& E, const PG8_LAS float* mid = nullptr) {
;     ...
;             PG8_WAIT_V(8); PG8_WAIT_L(0); PG8_BAR; PG8_MMA(1, 0, At, B0); PG8_MMA(1, 1, At, B1); PG8_BAR; PG8_SCHED;
;             PG8_LDB(B0, 1, 0); PG8_LDB(B1, 1, 1); PG8_SCHED; PG8_LDA(At, 1, 0); PG8_STAGE(PG8_SA(0, 1), a2 + hstepA, voffA);
;             PG8_WAIT_V(8); PG8_WAIT_L(0); PG8_BAR; PG8_MMA(0, 0, At, B0); PG8_MMA(0, 1, At, B1); PG8_BAR; PG8_SCHED;
	s_waitcnt lgkmcnt(0)
	v_mfma_f32_16x16x32_bf16 v[60:63], v[142:145], v[190:193], v[60:63]
	v_mfma_f32_16x16x32_bf16 v[56:59], v[154:157], v[190:193], v[56:59]
	v_mfma_f32_16x16x32_bf16 v[52:55], v[142:145], v[198:201], v[52:55]
	v_mfma_f32_16x16x32_bf16 v[44:47], v[154:157], v[198:201], v[44:47]
	v_mfma_f32_16x16x32_bf16 v[36:39], v[142:145], v[220:223], v[36:39]
	v_mfma_f32_16x16x32_bf16 v[28:31], v[154:157], v[220:223], v[28:31]
	v_mfma_f32_16x16x32_bf16 v[20:23], v[142:145], v[228:231], v[20:23]
	v_mfma_f32_16x16x32_bf16 v[12:15], v[154:157], v[228:231], v[12:15]
	v_mfma_f32_16x16x32_bf16 v[60:63], v[150:153], v[194:197], v[60:63]
	v_mfma_f32_16x16x32_bf16 v[56:59], v[158:161], v[194:197], v[56:59]
	v_mfma_f32_16x16x32_bf16 v[52:55], v[150:153], v[202:205], v[52:55]
	v_mfma_f32_16x16x32_bf16 v[44:47], v[158:161], v[202:205], v[44:47]
	v_mfma_f32_16x16x32_bf16 v[36:39], v[150:153], v[224:227], v[36:39]
	v_mfma_f32_16x16x32_bf16 v[28:31], v[158:161], v[224:227], v[28:31]
	v_mfma_f32_16x16x32_bf16 v[20:23], v[150:153], v[232:235], v[20:23]
	v_mfma_f32_16x16x32_bf16 v[12:15], v[158:161], v[232:235], v[12:15]
	v_mfma_f32_16x16x32_bf16 v[48:51], v[174:177], v[190:193], v[48:51]
	v_mfma_f32_16x16x32_bf16 v[40:43], v[182:185], v[190:193], v[40:43]
	v_mfma_f32_16x16x32_bf16 v[32:35], v[174:177], v[198:201], v[32:35]
	v_mfma_f32_16x16x32_bf16 v[24:27], v[182:185], v[198:201], v[24:27]
	v_mfma_f32_16x16x32_bf16 v[16:19], v[174:177], v[220:223], v[16:19]
	v_mfma_f32_16x16x32_bf16 v[8:11], v[182:185], v[220:223], v[8:11]
	v_mfma_f32_16x16x32_bf16 v[4:7], v[174:177], v[228:231], v[4:7]
	v_mfma_f32_16x16x32_bf16 v[0:3], v[182:185], v[228:231], v[0:3]
	v_mfma_f32_16x16x32_bf16 v[48:51], v[178:181], v[194:197], v[48:51]
	v_mfma_f32_16x16x32_bf16 v[40:43], v[186:189], v[194:197], v[40:43]
	v_mfma_f32_16x16x32_bf16 v[32:35], v[178:181], v[202:205], v[32:35]
	v_mfma_f32_16x16x32_bf16 v[24:27], v[186:189], v[202:205], v[24:27]
	v_mfma_f32_16x16x32_bf16 v[16:19], v[178:181], v[224:227], v[16:19]
	v_mfma_f32_16x16x32_bf16 v[8:11], v[186:189], v[224:227], v[8:11]
	v_mfma_f32_16x16x32_bf16 v[4:7], v[178:181], v[232:235], v[4:7]
	v_mfma_f32_16x16x32_bf16 v[0:3], v[186:189], v[232:235], v[0:3]
	s_barrier
	s_add_i32 s3, 0, 0x18000
	v_add_u32_e32 v140, s3, v146
	s_add_i32 s66, 0, 0x1c000
	ds_read_b128 v[142:145], v140
	ds_read_b128 v[150:153], v140 offset:1024
	ds_read_b128 v[154:157], v140 offset:2048
	ds_read_b128 v[158:161], v140 offset:3072
	v_add_u32_e32 v140, s66, v146
	ds_read_b128 v[174:177], v140
	ds_read_b128 v[178:181], v140 offset:1024
	ds_read_b128 v[182:185], v140 offset:2048
	ds_read_b128 v[186:189], v140 offset:3072
	s_add_u32 s50, s50, 0x40000
	s_addc_u32 s51, s51, 0
	s_mov_b32 m0, s55
	v_lshl_add_u64 v[244:245], s[50:51], 0, v[134:135]
	ds_read_b128 v[190:193], v148 offset:32768
	ds_read_b128 v[194:197], v148 offset:33792
	ds_read_b128 v[198:201], v148 offset:34816
	ds_read_b128 v[202:205], v148 offset:35840
	ds_read_b128 v[220:223], v148 offset:36864
	ds_read_b128 v[224:227], v148 offset:37888
	ds_read_b128 v[228:231], v148 offset:38912
	ds_read_b128 v[232:235], v148 offset:39936
	global_load_lds_dwordx4 v[244:245], off
	v_lshl_add_u64 v[244:245], s[50:51], 0, v[132:133]
	s_mov_b32 m0, s56
	s_nop 0
	global_load_lds_dwordx4 v[244:245], off
	s_waitcnt vmcnt(8)
	s_waitcnt lgkmcnt(0)
	s_barrier
	s_waitcnt lgkmcnt(0)
	v_mfma_f32_16x16x32_bf16 v[126:129], v[142:145], v[190:193], v[126:129]
	v_mfma_f32_16x16x32_bf16 v[122:125], v[154:157], v[190:193], v[122:125]
	v_mfma_f32_16x16x32_bf16 v[118:121], v[142:145], v[198:201], v[118:121]
	v_mfma_f32_16x16x32_bf16 v[110:113], v[154:157], v[198:201], v[110:113]
	v_mfma_f32_16x16x32_bf16 v[102:105], v[142:145], v[220:223], v[102:105]
	v_mfma_f32_16x16x32_bf16 v[94:97], v[154:157], v[220:223], v[94:97]
	v_mfma_f32_16x16x32_bf16 v[86:89], v[142:145], v[228:231], v[86:89]
	v_mfma_f32_16x16x32_bf16 v[76:79], v[154:157], v[228:231], v[76:79]
	v_mfma_f32_16x16x32_bf16 v[126:129], v[150:153], v[194:197], v[126:129]
	v_mfma_f32_16x16x32_bf16 v[122:125], v[158:161], v[194:197], v[122:125]
	v_mfma_f32_16x16x32_bf16 v[118:121], v[150:153], v[202:205], v[118:121]
	v_mfma_f32_16x16x32_bf16 v[110:113], v[158:161], v[202:205], v[110:113]
	v_mfma_f32_16x16x32_bf16 v[102:105], v[150:153], v[224:227], v[102:105]
	v_mfma_f32_16x16x32_bf16 v[94:97], v[158:161], v[224:227], v[94:97]
	v_mfma_f32_16x16x32_bf16 v[86:89], v[150:153], v[232:235], v[86:89]
	v_mfma_f32_16x16x32_bf16 v[76:79], v[158:161], v[232:235], v[76:79]
	v_mfma_f32_16x16x32_bf16 v[114:117], v[174:177], v[190:193], v[114:117]
	v_mfma_f32_16x16x32_bf16 v[106:109], v[182:185], v[190:193], v[106:109]
	v_mfma_f32_16x16x32_bf16 v[98:101], v[174:177], v[198:201], v[98:101]
	v_mfma_f32_16x16x32_bf16 v[90:93], v[182:185], v[198:201], v[90:93]
	v_mfma_f32_16x16x32_bf16 v[82:85], v[174:177], v[220:223], v[82:85]
	v_mfma_f32_16x16x32_bf16 v[72:75], v[182:185], v[220:223], v[72:75]
	v_mfma_f32_16x16x32_bf16 v[68:71], v[174:177], v[228:231], v[68:71]
	v_mfma_f32_16x16x32_bf16 v[64:67], v[182:185], v[228:231], v[64:67]
	v_mfma_f32_16x16x32_bf16 v[114:117], v[178:181], v[194:197], v[114:117]
	v_mfma_f32_16x16x32_bf16 v[106:109], v[186:189], v[194:197], v[106:109]
	v_mfma_f32_16x16x32_bf16 v[98:101], v[178:181], v[202:205], v[98:101]
	v_mfma_f32_16x16x32_bf16 v[90:93], v[186:189], v[202:205], v[90:93]
	v_mfma_f32_16x16x32_bf16 v[82:85], v[178:181], v[224:227], v[82:85]
	v_mfma_f32_16x16x32_bf16 v[72:75], v[186:189], v[224:227], v[72:75]
	v_mfma_f32_16x16x32_bf16 v[68:71], v[178:181], v[232:235], v[68:71]
	v_mfma_f32_16x16x32_bf16 v[64:67], v[186:189], v[232:235], v[64:67]
	s_barrier
; #define PG8_STAGE(bufoff, gbase, voff) do { _Pragma("unroll") for (int _i = 0; _i < 2; ++_i) \
;         __builtin_amdgcn_global_load_lds((const unsigned*)((const char*)(gbase) + (voff)[_i]), (PG8_LAS unsigned*)(lds + (bufoff) + ldsw + _i * 8192), 16, 0, 0); } while (0)
; #define PG8_LDA(dst, b, h) do { _Pragma("unroll") for (int m = 0; m < 4; ++m) _Pragma("unroll") for (int k = 0; k < 2; ++k) dst[m][k] = *(const PG8_LAS bf16x8*)(lds + PG8_SA(b, h) + aoff + m * 2048 + k * 1024); } while (0)
; #define PG8_MMA(ai, bj, At, Bt) do { __builtin_amdgcn_s_setprio(1); _Pragma("unroll") for (int m = 0; m < 4; ++m) _Pragma("unroll") for (int n = 0; n < 2; ++n) _Pragma("unroll") for (int k = 0; k < 2; ++k) \
;         acc[ai][bj][m][n] = __builtin_amdgcn_mfma_f32_16x16x32_bf16(Bt[n][k], At[m][k], acc[ai][bj][m][n], 0, 0, 0); __builtin_amdgcn_s_setprio(0); } while (0)
; #define PG8_WAIT_V(n) asm volatile("s_waitcnt vmcnt(" #n ")" ::: "memory")
; #define PG8_WAIT_L(n) asm volatile("s_waitcnt lgkmcnt(" #n ")" ::: "memory")
; #define PG8_BAR __builtin_amdgcn_s_barrier()
; #define PG8_SCHED __builtin_amdgcn_sched_barrier(0)
; template <class Epi, class Sched, bool ALIGN_EPI = false, bool SP2 = false, bool MID = false>
; __device__ __forceinline__ void gemm_phase(PG8_LAS unsigned char* lds, const Gemm g, const Sched& S, const Epi& E, const PG8_LAS float* mid = nullptr) {
;     ...
;         for (int t = 0; t < nt; t += 2) {
;     ...
;             PG8_LDA(At, 1, 1); PG8_STAGE(PG8_SB(1, 0), b3, voffB); PG8_STAGE(PG8_SB(1, 1), b3 + hstepB, voffB); PG8_STAGE(PG8_SA(1, 0), a3, voffA);
;             PG8_WAIT_V(8); PG8_WAIT_L(0); PG8_BAR; PG8_MMA(1, 0, At, B0); PG8_MMA(1, 1, At, B1); PG8_BAR; PG8_SCHED;
	s_add_i32 s3, s3, s52
	v_lshl_add_u64 v[236:237], v[236:237], 0, s[16:17]
	s_mov_b32 m0, s3
	ds_read_b128 v[190:193], v148 offset:49152
	ds_read_b128 v[194:197], v148 offset:50176
	ds_read_b128 v[198:201], v148 offset:51200
	ds_read_b128 v[202:205], v148 offset:52224
	ds_read_b128 v[220:223], v148 offset:53248
	ds_read_b128 v[224:227], v148 offset:54272
	ds_read_b128 v[228:231], v148 offset:55296
	ds_read_b128 v[232:235], v148 offset:56320
	global_load_lds_dwordx4 v[236:237], off
	s_add_i32 m0, s3, 0x2000
	s_add_u32 s48, s48, 0x40080
	v_lshl_add_u64 v[236:237], v[238:239], 0, s[16:17]
	s_addc_u32 s49, s49, 0
	s_add_i32 s3, s66, s52
	global_load_lds_dwordx4 v[236:237], off
	v_lshl_add_u64 v[236:237], s[48:49], 0, v[80:81]
	s_mov_b32 m0, s3
	s_nop 0
	global_load_lds_dwordx4 v[236:237], off
	v_lshl_add_u64 v[236:237], s[48:49], 0, v[130:131]
	s_add_i32 m0, s3, 0x2000
	s_nop 0
	global_load_lds_dwordx4 v[236:237], off
	v_lshl_add_u64 v[236:237], v[240:241], 0, s[16:17]
	s_mov_b32 m0, s10
	s_nop 0
	global_load_lds_dwordx4 v[236:237], off
	v_lshl_add_u64 v[236:237], v[242:243], 0, s[16:17]
	s_mov_b32 m0, s57
	s_nop 0
	global_load_lds_dwordx4 v[236:237], off
	s_waitcnt vmcnt(8)
	s_waitcnt lgkmcnt(0)
	s_barrier
	s_waitcnt lgkmcnt(0)
	v_mfma_f32_16x16x32_bf16 v[60:63], v[142:145], v[190:193], v[60:63]
	v_mfma_f32_16x16x32_bf16 v[56:59], v[154:157], v[190:193], v[56:59]
	v_mfma_f32_16x16x32_bf16 v[52:55], v[142:145], v[198:201], v[52:55]
	v_mfma_f32_16x16x32_bf16 v[44:47], v[154:157], v[198:201], v[44:47]
	v_mfma_f32_16x16x32_bf16 v[36:39], v[142:145], v[220:223], v[36:39]
	v_mfma_f32_16x16x32_bf16 v[28:31], v[154:157], v[220:223], v[28:31]
	v_mfma_f32_16x16x32_bf16 v[20:23], v[142:145], v[228:231], v[20:23]
	v_mfma_f32_16x16x32_bf16 v[12:15], v[154:157], v[228:231], v[12:15]
	v_mfma_f32_16x16x32_bf16 v[60:63], v[150:153], v[194:197], v[60:63]
	v_mfma_f32_16x16x32_bf16 v[56:59], v[158:161], v[194:197], v[56:59]
	v_mfma_f32_16x16x32_bf16 v[52:55], v[150:153], v[202:205], v[52:55]
	v_mfma_f32_16x16x32_bf16 v[44:47], v[158:161], v[202:205], v[44:47]
	v_mfma_f32_16x16x32_bf16 v[36:39], v[150:153], v[224:227], v[36:39]
	v_mfma_f32_16x16x32_bf16 v[28:31], v[158:161], v[224:227], v[28:31]
	v_mfma_f32_16x16x32_bf16 v[20:23], v[150:153], v[232:235], v[20:23]
	v_mfma_f32_16x16x32_bf16 v[12:15], v[158:161], v[232:235], v[12:15]
	v_mfma_f32_16x16x32_bf16 v[48:51], v[174:177], v[190:193], v[48:51]
	v_mfma_f32_16x16x32_bf16 v[40:43], v[182:185], v[190:193], v[40:43]
	v_mfma_f32_16x16x32_bf16 v[32:35], v[174:177], v[198:201], v[32:35]
	v_mfma_f32_16x16x32_bf16 v[24:27], v[182:185], v[198:201], v[24:27]
	v_mfma_f32_16x16x32_bf16 v[16:19], v[174:177], v[220:223], v[16:19]
	v_mfma_f32_16x16x32_bf16 v[8:11], v[182:185], v[220:223], v[8:11]
	v_mfma_f32_16x16x32_bf16 v[4:7], v[174:177], v[228:231], v[4:7]
	v_mfma_f32_16x16x32_bf16 v[0:3], v[182:185], v[228:231], v[0:3]
	v_mfma_f32_16x16x32_bf16 v[48:51], v[178:181], v[194:197], v[48:51]
	v_mfma_f32_16x16x32_bf16 v[40:43], v[186:189], v[194:197], v[40:43]
	v_mfma_f32_16x16x32_bf16 v[32:35], v[178:181], v[202:205], v[32:35]
	v_mfma_f32_16x16x32_bf16 v[24:27], v[186:189], v[202:205], v[24:27]
	v_mfma_f32_16x16x32_bf16 v[16:19], v[178:181], v[224:227], v[16:19]
	v_mfma_f32_16x16x32_bf16 v[8:11], v[186:189], v[224:227], v[8:11]
	v_mfma_f32_16x16x32_bf16 v[4:7], v[178:181], v[232:235], v[4:7]
	v_mfma_f32_16x16x32_bf16 v[0:3], v[186:189], v[232:235], v[0:3]
	s_barrier
	s_add_i32 s65, s65, 2
	s_add_u32 s12, s12, 0x100
	s_addc_u32 s13, s13, 0
	s_add_u32 s63, s63, 0x100
	s_addc_u32 s64, s64, 0
	s_cmp_gt_u32 s65, 13
	s_cbranch_scc0 .LBB0_192
	s_and_b64 vcc, exec, s[20:21]
	s_cbranch_vccz .LBB0_195
	s_barrier

; #define PG8_STAGE(bufoff, gbase, voff) do { _Pragma("unroll") for (int _i = 0; _i < 2; ++_i) \
;         __builtin_amdgcn_global_load_lds((const unsigned*)((const char*)(gbase) + (voff)[_i]), (PG8_LAS unsigned*)(lds + (bufoff) + ldsw + _i * 8192), 16, 0, 0); } while (0)
; #define PG8_LDA(dst, b, h) do { _Pragma("unroll") for (int m = 0; m < 4; ++m) _Pragma("unroll") for (int k = 0; k < 2; ++k) dst[m][k] = *(const PG8_LAS bf16x8*)(lds + PG8_SA(b, h) + aoff + m * 2048 + k * 1024); } while (0)
; #define PG8_LDB(dst, b, h) do { _Pragma("unroll") for (int n = 0; n < 2; ++n) _Pragma("unroll") for (int k = 0; k < 2; ++k) dst[n][k] = *(const PG8_LAS bf16x8*)(lds + PG8_SB(b, h) + boff + n * 2048 + k * 1024); } while (0)
; #define PG8_MMA(ai, bj, At, Bt) do { __builtin_amdgcn_s_setprio(1); _Pragma("unroll") for (int m = 0; m < 4; ++m) _Pragma("unroll") for (int n = 0; n < 2; ++n) _Pragma("unroll") for (int k = 0; k < 2; ++k) \
;         acc[ai][bj][m][n] = __builtin_amdgcn_mfma_f32_16x16x32_bf16(Bt[n][k], At[m][k], acc[ai][bj][m][n], 0, 0, 0); __builtin_amdgcn_s_setprio(0); } while (0)
; #define PG8_WAIT_V(n) asm volatile("s_waitcnt vmcnt(" #n ")" ::: "memory")
; #define PG8_WAIT_L(n) asm volatile("s_waitcnt lgkmcnt(" #n ")" ::: "memory")
; #define PG8_BAR __builtin_amdgcn_s_barrier()
; #define PG8_SCHED __builtin_amdgcn_sched_barrier(0)
; template <class Epi, class Sched, bool ALIGN_EPI = false, bool SP2 = false, bool MID = false>
; __device__ __forceinline__ void gemm_phase(PG8_LAS unsigned char* lds, const Gemm g, const Sched& S, const Epi& E, const PG8_LAS float* mid = nullptr) {
;     ...
;             if constexpr (SP2) {
;             PG8_LDB(B0, 0, 0); PG8_LDB(B1, 0, 1); PG8_SCHED; PG8_LDA(At, 0, 0); PG8_STAGE(PG8_SA(1, 1), a1 + hstepA, voffA);
;             PG8_WAIT_V(8); PG8_WAIT_L(0); PG8_BAR; PG8_MMA(0, 0, At, B0); PG8_MMA(0, 1, At, B1); PG8_BAR; PG8_SCHED;
;             PG8_LDA(At, 0, 1); PG8_STAGE(PG8_SB(0, 0), b2, voffB); PG8_STAGE(PG8_SB(0, 1), b2 + hstepB, voffB); PG8_STAGE(PG8_SA(0, 0), a2, voffA);
.LBB0_412:
	s_add_u32 s3, s14, s12
	s_addc_u32 s20, s15, s13
	s_add_u32 s3, s3, 0x100
	s_addc_u32 s20, s20, 0
	s_add_u32 s82, s79, s12
	s_addc_u32 s21, s80, s13
	s_add_i32 s83, 0, 0x10000
	s_cmpk_eq_i32 s12, 0x700
	s_cselect_b32 s55, s49, s20
	s_cselect_b32 s54, s71, s3
	v_add_u32_e32 v53, s83, v199
	s_cselect_b32 s21, s47, s21
	s_cselect_b32 s20, s78, s82
	s_add_i32 s3, 0, 0x14000
	ds_read_b128 v[54:57], v53
	ds_read_b128 v[58:61], v53 offset:1024
	ds_read_b128 v[174:177], v53 offset:2048
	ds_read_b128 v[178:181], v53 offset:3072
	v_add_u32_e32 v53, s3, v199
	ds_read_b128 v[182:185], v53
	ds_read_b128 v[186:189], v53 offset:1024
	ds_read_b128 v[190:193], v53 offset:2048
	ds_read_b128 v[194:197], v53 offset:3072
	v_lshl_add_u64 v[62:63], v[50:51], 0, s[12:13]
	s_add_i32 m0, s19, 0xc000
	ds_read_b128 v[220:223], v204
	ds_read_b128 v[224:227], v204 offset:1024
	ds_read_b128 v[228:231], v204 offset:2048
	ds_read_b128 v[232:235], v204 offset:3072
	ds_read_b128 v[236:239], v204 offset:4096
	ds_read_b128 v[240:243], v204 offset:5120
	ds_read_b128 v[244:247], v204 offset:6144
	ds_read_b128 v[248:251], v204 offset:7168
	global_load_lds_dwordx4 v[62:63], off
	v_lshl_add_u64 v[62:63], v[48:49], 0, s[12:13]
	s_add_i32 m0, s19, 0xe000
	s_nop 0
	global_load_lds_dwordx4 v[62:63], off
	s_waitcnt vmcnt(8)
	s_waitcnt lgkmcnt(0)
	s_barrier
	s_waitcnt lgkmcnt(0)
	v_mfma_f32_16x16x32_bf16 v[144:147], v[54:57], v[220:223], v[144:147]
	v_mfma_f32_16x16x32_bf16 v[140:143], v[174:177], v[220:223], v[140:143]
	v_mfma_f32_16x16x32_bf16 v[128:131], v[54:57], v[228:231], v[128:131]
	v_mfma_f32_16x16x32_bf16 v[124:127], v[174:177], v[228:231], v[124:127]
	v_mfma_f32_16x16x32_bf16 v[112:115], v[54:57], v[236:239], v[112:115]
	v_mfma_f32_16x16x32_bf16 v[108:111], v[174:177], v[236:239], v[108:111]
	v_mfma_f32_16x16x32_bf16 v[96:99], v[54:57], v[244:247], v[96:99]
	v_mfma_f32_16x16x32_bf16 v[92:95], v[174:177], v[244:247], v[92:95]
	v_mfma_f32_16x16x32_bf16 v[144:147], v[58:61], v[224:227], v[144:147]
	v_mfma_f32_16x16x32_bf16 v[140:143], v[178:181], v[224:227], v[140:143]
	v_mfma_f32_16x16x32_bf16 v[128:131], v[58:61], v[232:235], v[128:131]
	v_mfma_f32_16x16x32_bf16 v[124:127], v[178:181], v[232:235], v[124:127]
	v_mfma_f32_16x16x32_bf16 v[112:115], v[58:61], v[240:243], v[112:115]
	v_mfma_f32_16x16x32_bf16 v[108:111], v[178:181], v[240:243], v[108:111]
	v_mfma_f32_16x16x32_bf16 v[96:99], v[58:61], v[248:251], v[96:99]
	v_mfma_f32_16x16x32_bf16 v[92:95], v[178:181], v[248:251], v[92:95]
	v_mfma_f32_16x16x32_bf16 v[136:139], v[182:185], v[220:223], v[136:139]
	v_mfma_f32_16x16x32_bf16 v[132:135], v[190:193], v[220:223], v[132:135]
	v_mfma_f32_16x16x32_bf16 v[120:123], v[182:185], v[228:231], v[120:123]
	v_mfma_f32_16x16x32_bf16 v[116:119], v[190:193], v[228:231], v[116:119]
	v_mfma_f32_16x16x32_bf16 v[104:107], v[182:185], v[236:239], v[104:107]
	v_mfma_f32_16x16x32_bf16 v[100:103], v[190:193], v[236:239], v[100:103]
	v_mfma_f32_16x16x32_bf16 v[88:91], v[182:185], v[244:247], v[88:91]
	v_mfma_f32_16x16x32_bf16 v[82:85], v[190:193], v[244:247], v[84:87]
	v_mfma_f32_16x16x32_bf16 v[136:139], v[186:189], v[224:227], v[136:139]
	v_mfma_f32_16x16x32_bf16 v[132:135], v[194:197], v[224:227], v[132:135]
	v_mfma_f32_16x16x32_bf16 v[120:123], v[186:189], v[232:235], v[120:123]
	v_mfma_f32_16x16x32_bf16 v[116:119], v[194:197], v[232:235], v[116:119]
	v_mfma_f32_16x16x32_bf16 v[104:107], v[186:189], v[240:243], v[104:107]
	v_mfma_f32_16x16x32_bf16 v[100:103], v[194:197], v[240:243], v[100:103]
	v_mfma_f32_16x16x32_bf16 v[88:91], v[186:189], v[248:251], v[88:91]
	v_mfma_f32_16x16x32_bf16 v[82:85], v[194:197], v[248:251], v[82:85]
	s_barrier
	s_add_i32 s82, s83, s2
	v_lshl_add_u64 v[160:161], s[20:21], 0, v[150:151]
	s_mov_b32 m0, s82
	ds_read_b128 v[220:223], v204 offset:16384
	ds_read_b128 v[224:227], v204 offset:17408
	ds_read_b128 v[228:231], v204 offset:18432
	ds_read_b128 v[232:235], v204 offset:19456
	ds_read_b128 v[236:239], v204 offset:20480
	ds_read_b128 v[240:243], v204 offset:21504
	ds_read_b128 v[244:247], v204 offset:22528
	ds_read_b128 v[248:251], v204 offset:23552
	global_load_lds_dwordx4 v[160:161], off
	s_add_i32 m0, s82, 0x2000
	s_add_u32 s82, s20, 0x40000
	v_lshl_add_u64 v[210:211], s[20:21], 0, v[154:155]
	s_addc_u32 s83, s21, 0
	s_add_i32 s3, s3, s2
	global_load_lds_dwordx4 v[210:211], off
	v_lshl_add_u64 v[62:63], s[82:83], 0, v[150:151]
	s_mov_b32 m0, s3
	v_lshl_add_u64 v[252:253], s[54:55], 0, v[148:149]
	global_load_lds_dwordx4 v[62:63], off
	v_lshl_add_u64 v[62:63], s[82:83], 0, v[154:155]
	s_add_i32 m0, s3, 0x2000
	v_lshl_add_u64 v[212:213], s[54:55], 0, v[152:153]
	global_load_lds_dwordx4 v[62:63], off
	s_mov_b32 m0, s19
	s_nop 0
	global_load_lds_dwordx4 v[252:253], off
	s_mov_b32 m0, s66
	s_nop 0
	global_load_lds_dwordx4 v[212:213], off
	s_waitcnt vmcnt(8)
	s_waitcnt lgkmcnt(0)
	s_barrier
; #define PG8_STAGE(bufoff, gbase, voff) do { _Pragma("unroll") for (int _i = 0; _i < 2; ++_i) \
;         __builtin_amdgcn_global_load_lds((const unsigned*)((const char*)(gbase) + (voff)[_i]), (PG8_LAS unsigned*)(lds + (bufoff) + ldsw + _i * 8192), 16, 0, 0); } while (0)
; #define PG8_LDA(dst, b, h) do { _Pragma("unroll") for (int m = 0; m < 4; ++m) _Pragma("unroll") for (int k = 0; k < 2; ++k) dst[m][k] = *(const PG8_LAS bf16x8*)(lds + PG8_SA(b, h) + aoff + m * 2048 + k * 1024); } while (0)
; #define PG8_LDB(dst, b, h) do { _Pragma("unroll") for (int n = 0; n < 2; ++n) _Pragma("unroll") for (int k = 0; k < 2; ++k) dst[n][k] = *(const PG8_LAS bf16x8*)(lds + PG8_SB(b, h) + boff + n * 2048 + k * 1024); } while (0)
; #define PG8_MMA(ai, bj, At, Bt) do { __builtin_amdgcn_s_setprio(1); _Pragma("unroll") for (int m = 0; m < 4; ++m) _Pragma("unroll") for (int n = 0; n < 2; ++n) _Pragma("unroll") for (int k = 0; k < 2; ++k) \
;         acc[ai][bj][m][n] = __builtin_amdgcn_mfma_f32_16x16x32_bf16(Bt[n][k], At[m][k], acc[ai][bj][m][n], 0, 0, 0); __builtin_amdgcn_s_setprio(0); } while (0)
; #define PG8_WAIT_V(n) asm volatile("s_waitcnt vmcnt(" #n ")" ::: "memory")
; #define PG8_WAIT_L(n) asm volatile("s_waitcnt lgkmcnt(" #n ")" ::: "memory")
; #define PG8_BAR __builtin_amdgcn_s_barrier()
; #define PG8_SCHED __builtin_amdgcn_sched_barrier(0)
; template <class Epi, class Sched, bool ALIGN_EPI = false, bool SP2 = false, bool MID = false>
; __device__ __forceinline__ void gemm_phase(PG8_LAS unsigned char* lds, const Gemm g, const Sched& S, const Epi& E, const PG8_LAS float* mid = nullptr) {
;     ...
;             PG8_WAIT_V(8); PG8_WAIT_L(0); PG8_BAR; PG8_MMA(1, 0, At, B0); PG8_MMA(1, 1, At, B1); PG8_BAR; PG8_SCHED;
;             PG8_LDB(B0, 1, 0); PG8_LDB(B1, 1, 1); PG8_SCHED; PG8_LDA(At, 1, 0); PG8_STAGE(PG8_SA(0, 1), a2 + hstepA, voffA);
;             PG8_WAIT_V(8); PG8_WAIT_L(0); PG8_BAR; PG8_MMA(0, 0, At, B0); PG8_MMA(0, 1, At, B1); PG8_BAR; PG8_SCHED;
	s_waitcnt lgkmcnt(0)
	v_mfma_f32_16x16x32_bf16 v[76:79], v[54:57], v[220:223], v[76:79]
	v_mfma_f32_16x16x32_bf16 v[72:75], v[174:177], v[220:223], v[72:75]
	v_mfma_f32_16x16x32_bf16 v[44:47], v[54:57], v[228:231], v[44:47]
	v_mfma_f32_16x16x32_bf16 v[40:43], v[174:177], v[228:231], v[40:43]
	v_mfma_f32_16x16x32_bf16 v[28:31], v[54:57], v[236:239], v[28:31]
	v_mfma_f32_16x16x32_bf16 v[24:27], v[174:177], v[236:239], v[24:27]
	v_mfma_f32_16x16x32_bf16 v[12:15], v[54:57], v[244:247], v[12:15]
	v_mfma_f32_16x16x32_bf16 v[8:11], v[174:177], v[244:247], v[8:11]
	v_mfma_f32_16x16x32_bf16 v[76:79], v[58:61], v[224:227], v[76:79]
	v_mfma_f32_16x16x32_bf16 v[72:75], v[178:181], v[224:227], v[72:75]
	v_mfma_f32_16x16x32_bf16 v[44:47], v[58:61], v[232:235], v[44:47]
	v_mfma_f32_16x16x32_bf16 v[40:43], v[178:181], v[232:235], v[40:43]
	v_mfma_f32_16x16x32_bf16 v[28:31], v[58:61], v[240:243], v[28:31]
	v_mfma_f32_16x16x32_bf16 v[24:27], v[178:181], v[240:243], v[24:27]
	v_mfma_f32_16x16x32_bf16 v[12:15], v[58:61], v[248:251], v[12:15]
	v_mfma_f32_16x16x32_bf16 v[8:11], v[178:181], v[248:251], v[8:11]
	v_mfma_f32_16x16x32_bf16 v[36:39], v[182:185], v[228:231], v[36:39]
	v_mfma_f32_16x16x32_bf16 v[32:35], v[190:193], v[228:231], v[32:35]
	v_mfma_f32_16x16x32_bf16 v[20:23], v[182:185], v[236:239], v[20:23]
	v_mfma_f32_16x16x32_bf16 v[16:19], v[190:193], v[236:239], v[16:19]
	v_mfma_f32_16x16x32_bf16 v[4:7], v[182:185], v[244:247], v[4:7]
	v_mfma_f32_16x16x32_bf16 v[0:3], v[190:193], v[244:247], v[0:3]
	v_mfma_f32_16x16x32_bf16 v[54:57], v[182:185], v[220:223], v[68:71]
	v_mfma_f32_16x16x32_bf16 v[58:61], v[190:193], v[220:223], v[64:67]
	v_mfma_f32_16x16x32_bf16 v[36:39], v[186:189], v[232:235], v[36:39]
	v_mfma_f32_16x16x32_bf16 v[32:35], v[194:197], v[232:235], v[32:35]
	v_mfma_f32_16x16x32_bf16 v[20:23], v[186:189], v[240:243], v[20:23]
	v_mfma_f32_16x16x32_bf16 v[16:19], v[194:197], v[240:243], v[16:19]
	v_mfma_f32_16x16x32_bf16 v[4:7], v[186:189], v[248:251], v[4:7]
	v_mfma_f32_16x16x32_bf16 v[0:3], v[194:197], v[248:251], v[0:3]
	v_mfma_f32_16x16x32_bf16 v[54:57], v[186:189], v[224:227], v[54:57]
	v_mfma_f32_16x16x32_bf16 v[58:61], v[194:197], v[224:227], v[58:61]
	s_barrier
	s_add_i32 s3, 0, 0x18000
	v_add_u32_e32 v53, s3, v199
	s_add_i32 s82, 0, 0x1c000
	ds_read_b128 v[62:65], v53
	ds_read_b128 v[66:69], v53 offset:1024
	ds_read_b128 v[174:177], v53 offset:2048
	ds_read_b128 v[178:181], v53 offset:3072
	v_add_u32_e32 v53, s82, v199
	ds_read_b128 v[182:185], v53
	ds_read_b128 v[186:189], v53 offset:1024
	ds_read_b128 v[190:193], v53 offset:2048
	ds_read_b128 v[194:197], v53 offset:3072
	s_add_u32 s54, s54, 0x40000
	s_addc_u32 s55, s55, 0
	s_mov_b32 m0, s67
	v_lshl_add_u64 v[70:71], s[54:55], 0, v[148:149]
	ds_read_b128 v[220:223], v204 offset:32768
	ds_read_b128 v[224:227], v204 offset:33792
	ds_read_b128 v[228:231], v204 offset:34816
	ds_read_b128 v[232:235], v204 offset:35840
	ds_read_b128 v[236:239], v204 offset:36864
	ds_read_b128 v[240:243], v204 offset:37888
	ds_read_b128 v[244:247], v204 offset:38912
	ds_read_b128 v[248:251], v204 offset:39936
	global_load_lds_dwordx4 v[70:71], off
	v_lshl_add_u64 v[70:71], s[54:55], 0, v[152:153]
	s_mov_b32 m0, s68
	s_nop 0
	global_load_lds_dwordx4 v[70:71], off
	s_waitcnt vmcnt(8)
	s_waitcnt lgkmcnt(0)
	s_barrier
	s_waitcnt lgkmcnt(0)
	v_mfma_f32_16x16x32_bf16 v[144:147], v[62:65], v[220:223], v[144:147]
	v_mfma_f32_16x16x32_bf16 v[140:143], v[174:177], v[220:223], v[140:143]
	v_mfma_f32_16x16x32_bf16 v[128:131], v[62:65], v[228:231], v[128:131]
	v_mfma_f32_16x16x32_bf16 v[124:127], v[174:177], v[228:231], v[124:127]
	v_mfma_f32_16x16x32_bf16 v[112:115], v[62:65], v[236:239], v[112:115]
	v_mfma_f32_16x16x32_bf16 v[108:111], v[174:177], v[236:239], v[108:111]
	v_mfma_f32_16x16x32_bf16 v[96:99], v[62:65], v[244:247], v[96:99]
	v_mfma_f32_16x16x32_bf16 v[92:95], v[174:177], v[244:247], v[92:95]
	v_mfma_f32_16x16x32_bf16 v[144:147], v[66:69], v[224:227], v[144:147]
	v_mfma_f32_16x16x32_bf16 v[140:143], v[178:181], v[224:227], v[140:143]
	v_mfma_f32_16x16x32_bf16 v[128:131], v[66:69], v[232:235], v[128:131]
	v_mfma_f32_16x16x32_bf16 v[124:127], v[178:181], v[232:235], v[124:127]
	v_mfma_f32_16x16x32_bf16 v[112:115], v[66:69], v[240:243], v[112:115]
	v_mfma_f32_16x16x32_bf16 v[108:111], v[178:181], v[240:243], v[108:111]
	v_mfma_f32_16x16x32_bf16 v[96:99], v[66:69], v[248:251], v[96:99]
	v_mfma_f32_16x16x32_bf16 v[92:95], v[178:181], v[248:251], v[92:95]
	v_mfma_f32_16x16x32_bf16 v[136:139], v[182:185], v[220:223], v[136:139]
	v_mfma_f32_16x16x32_bf16 v[132:135], v[190:193], v[220:223], v[132:135]
	v_mfma_f32_16x16x32_bf16 v[120:123], v[182:185], v[228:231], v[120:123]
	v_mfma_f32_16x16x32_bf16 v[116:119], v[190:193], v[228:231], v[116:119]
	v_mfma_f32_16x16x32_bf16 v[104:107], v[182:185], v[236:239], v[104:107]
	v_mfma_f32_16x16x32_bf16 v[100:103], v[190:193], v[236:239], v[100:103]
	v_mfma_f32_16x16x32_bf16 v[86:89], v[182:185], v[244:247], v[88:91]
	v_mfma_f32_16x16x32_bf16 v[82:85], v[190:193], v[244:247], v[82:85]
	v_mfma_f32_16x16x32_bf16 v[136:139], v[186:189], v[224:227], v[136:139]
	v_mfma_f32_16x16x32_bf16 v[132:135], v[194:197], v[224:227], v[132:135]
	v_mfma_f32_16x16x32_bf16 v[120:123], v[186:189], v[232:235], v[120:123]
	v_mfma_f32_16x16x32_bf16 v[116:119], v[194:197], v[232:235], v[116:119]
	v_mfma_f32_16x16x32_bf16 v[104:107], v[186:189], v[240:243], v[104:107]
	v_mfma_f32_16x16x32_bf16 v[100:103], v[194:197], v[240:243], v[100:103]
	v_mfma_f32_16x16x32_bf16 v[88:91], v[186:189], v[248:251], v[86:89]
	v_mfma_f32_16x16x32_bf16 v[84:87], v[194:197], v[248:251], v[82:85]
	s_barrier
; #define PG8_STAGE(bufoff, gbase, voff) do { _Pragma("unroll") for (int _i = 0; _i < 2; ++_i) \
;         __builtin_amdgcn_global_load_lds((const unsigned*)((const char*)(gbase) + (voff)[_i]), (PG8_LAS unsigned*)(lds + (bufoff) + ldsw + _i * 8192), 16, 0, 0); } while (0)
; #define PG8_LDA(dst, b, h) do { _Pragma("unroll") for (int m = 0; m < 4; ++m) _Pragma("unroll") for (int k = 0; k < 2; ++k) dst[m][k] = *(const PG8_LAS bf16x8*)(lds + PG8_SA(b, h) + aoff + m * 2048 + k * 1024); } while (0)
; #define PG8_MMA(ai, bj, At, Bt) do { __builtin_amdgcn_s_setprio(1); _Pragma("unroll") for (int m = 0; m < 4; ++m) _Pragma("unroll") for (int n = 0; n < 2; ++n) _Pragma("unroll") for (int k = 0; k < 2; ++k) \
;         acc[ai][bj][m][n] = __builtin_amdgcn_mfma_f32_16x16x32_bf16(Bt[n][k], At[m][k], acc[ai][bj][m][n], 0, 0, 0); __builtin_amdgcn_s_setprio(0); } while (0)
; #define PG8_WAIT_V(n) asm volatile("s_waitcnt vmcnt(" #n ")" ::: "memory")
; #define PG8_WAIT_L(n) asm volatile("s_waitcnt lgkmcnt(" #n ")" ::: "memory")
; #define PG8_BAR __builtin_amdgcn_s_barrier()
; #define PG8_SCHED __builtin_amdgcn_sched_barrier(0)
; template <class Epi, class Sched, bool ALIGN_EPI = false, bool SP2 = false, bool MID = false>
; __device__ __forceinline__ void gemm_phase(PG8_LAS unsigned char* lds, const Gemm g, const Sched& S, const Epi& E, const PG8_LAS float* mid = nullptr) {
;     ...
;         for (int t = 0; t < nt; t += 2) {
;     ...
;             PG8_LDA(At, 1, 1); PG8_STAGE(PG8_SB(1, 0), b3, voffB); PG8_STAGE(PG8_SB(1, 1), b3 + hstepB, voffB); PG8_STAGE(PG8_SA(1, 0), a3, voffA);
;             PG8_WAIT_V(8); PG8_WAIT_L(0); PG8_BAR; PG8_MMA(1, 0, At, B0); PG8_MMA(1, 1, At, B1); PG8_BAR; PG8_SCHED;
	s_add_i32 s3, s3, s2
	v_lshl_add_u64 v[70:71], v[160:161], 0, s[16:17]
	s_mov_b32 m0, s3
	ds_read_b128 v[220:223], v204 offset:49152
	ds_read_b128 v[224:227], v204 offset:50176
	ds_read_b128 v[228:231], v204 offset:51200
	ds_read_b128 v[232:235], v204 offset:52224
	ds_read_b128 v[236:239], v204 offset:53248
	ds_read_b128 v[240:243], v204 offset:54272
	ds_read_b128 v[244:247], v204 offset:55296
	ds_read_b128 v[248:251], v204 offset:56320
	global_load_lds_dwordx4 v[70:71], off
	s_add_i32 m0, s3, 0x2000
	s_add_u32 s20, s20, 0x40080
	v_lshl_add_u64 v[70:71], v[210:211], 0, s[16:17]
	s_addc_u32 s21, s21, 0
	s_add_i32 s3, s82, s2
	global_load_lds_dwordx4 v[70:71], off
	v_lshl_add_u64 v[70:71], s[20:21], 0, v[150:151]
	s_mov_b32 m0, s3
	s_nop 0
	global_load_lds_dwordx4 v[70:71], off
	v_lshl_add_u64 v[70:71], s[20:21], 0, v[154:155]
	s_add_i32 m0, s3, 0x2000
	s_nop 0
	global_load_lds_dwordx4 v[70:71], off
	v_lshl_add_u64 v[70:71], v[252:253], 0, s[16:17]
	s_mov_b32 m0, s10
	s_nop 0
	global_load_lds_dwordx4 v[70:71], off
	v_lshl_add_u64 v[70:71], v[212:213], 0, s[16:17]
	s_mov_b32 m0, s69
	s_nop 0
	global_load_lds_dwordx4 v[70:71], off
	s_waitcnt vmcnt(8)
	s_waitcnt lgkmcnt(0)
	s_barrier
	s_waitcnt lgkmcnt(0)
	v_mfma_f32_16x16x32_bf16 v[76:79], v[62:65], v[220:223], v[76:79]
	v_mfma_f32_16x16x32_bf16 v[70:73], v[174:177], v[220:223], v[72:75]
	v_mfma_f32_16x16x32_bf16 v[44:47], v[62:65], v[228:231], v[44:47]
	v_mfma_f32_16x16x32_bf16 v[40:43], v[174:177], v[228:231], v[40:43]
	v_mfma_f32_16x16x32_bf16 v[28:31], v[62:65], v[236:239], v[28:31]
	v_mfma_f32_16x16x32_bf16 v[24:27], v[174:177], v[236:239], v[24:27]
	v_mfma_f32_16x16x32_bf16 v[12:15], v[62:65], v[244:247], v[12:15]
	v_mfma_f32_16x16x32_bf16 v[8:11], v[174:177], v[244:247], v[8:11]
	v_mfma_f32_16x16x32_bf16 v[76:79], v[66:69], v[224:227], v[76:79]
	v_mfma_f32_16x16x32_bf16 v[72:75], v[178:181], v[224:227], v[70:73]
	v_mfma_f32_16x16x32_bf16 v[44:47], v[66:69], v[232:235], v[44:47]
	v_mfma_f32_16x16x32_bf16 v[40:43], v[178:181], v[232:235], v[40:43]
	v_mfma_f32_16x16x32_bf16 v[28:31], v[66:69], v[240:243], v[28:31]
	v_mfma_f32_16x16x32_bf16 v[24:27], v[178:181], v[240:243], v[24:27]
	v_mfma_f32_16x16x32_bf16 v[12:15], v[66:69], v[248:251], v[12:15]
	v_mfma_f32_16x16x32_bf16 v[8:11], v[178:181], v[248:251], v[8:11]
	v_mfma_f32_16x16x32_bf16 v[54:57], v[182:185], v[220:223], v[54:57]
	v_mfma_f32_16x16x32_bf16 v[68:71], v[186:189], v[224:227], v[54:57]
	v_mfma_f32_16x16x32_bf16 v[54:57], v[190:193], v[220:223], v[58:61]
	v_mfma_f32_16x16x32_bf16 v[36:39], v[182:185], v[228:231], v[36:39]
	v_mfma_f32_16x16x32_bf16 v[32:35], v[190:193], v[228:231], v[32:35]
	v_mfma_f32_16x16x32_bf16 v[20:23], v[182:185], v[236:239], v[20:23]
	v_mfma_f32_16x16x32_bf16 v[16:19], v[190:193], v[236:239], v[16:19]
	v_mfma_f32_16x16x32_bf16 v[4:7], v[182:185], v[244:247], v[4:7]
	v_mfma_f32_16x16x32_bf16 v[0:3], v[190:193], v[244:247], v[0:3]
	v_mfma_f32_16x16x32_bf16 v[64:67], v[194:197], v[224:227], v[54:57]
	v_mfma_f32_16x16x32_bf16 v[36:39], v[186:189], v[232:235], v[36:39]
	v_mfma_f32_16x16x32_bf16 v[32:35], v[194:197], v[232:235], v[32:35]
	v_mfma_f32_16x16x32_bf16 v[20:23], v[186:189], v[240:243], v[20:23]
	v_mfma_f32_16x16x32_bf16 v[16:19], v[194:197], v[240:243], v[16:19]
	v_mfma_f32_16x16x32_bf16 v[4:7], v[186:189], v[248:251], v[4:7]
	v_mfma_f32_16x16x32_bf16 v[0:3], v[194:197], v[248:251], v[0:3]
	s_barrier
	s_add_i32 s81, s81, 2
	s_add_u32 s12, s12, 0x100
	s_addc_u32 s13, s13, 0
	s_cmp_gt_u32 s81, 13
	s_cbranch_scc1 .LBB0_415

; #define PG8_STAGE(bufoff, gbase, voff) do { _Pragma("unroll") for (int _i = 0; _i < 2; ++_i) \
;         __builtin_amdgcn_global_load_lds((const unsigned*)((const char*)(gbase) + (voff)[_i]), (PG8_LAS unsigned*)(lds + (bufoff) + ldsw + _i * 8192), 16, 0, 0); } while (0)
; #define PG8_LDA(dst, b, h) do { _Pragma("unroll") for (int m = 0; m < 4; ++m) _Pragma("unroll") for (int k = 0; k < 2; ++k) dst[m][k] = *(const PG8_LAS bf16x8*)(lds + PG8_SA(b, h) + aoff + m * 2048 + k * 1024); } while (0)
; #define PG8_LDB(dst, b, h) do { _Pragma("unroll") for (int n = 0; n < 2; ++n) _Pragma("unroll") for (int k = 0; k < 2; ++k) dst[n][k] = *(const PG8_LAS bf16x8*)(lds + PG8_SB(b, h) + boff + n * 2048 + k * 1024); } while (0)
; #define PG8_MMA(ai, bj, At, Bt) do { __builtin_amdgcn_s_setprio(1); _Pragma("unroll") for (int m = 0; m < 4; ++m) _Pragma("unroll") for (int n = 0; n < 2; ++n) _Pragma("unroll") for (int k = 0; k < 2; ++k) \
;         acc[ai][bj][m][n] = __builtin_amdgcn_mfma_f32_16x16x32_bf16(Bt[n][k], At[m][k], acc[ai][bj][m][n], 0, 0, 0); __builtin_amdgcn_s_setprio(0); } while (0)
; #define PG8_WAIT_V(n) asm volatile("s_waitcnt vmcnt(" #n ")" ::: "memory")
; #define PG8_WAIT_L(n) asm volatile("s_waitcnt lgkmcnt(" #n ")" ::: "memory")
; #define PG8_BAR __builtin_amdgcn_s_barrier()
; #define PG8_SCHED __builtin_amdgcn_sched_barrier(0)
; template <class Epi, class Sched, bool ALIGN_EPI = false, bool SP2 = false, bool MID = false>
; __device__ __forceinline__ void gemm_phase(PG8_LAS unsigned char* lds, const Gemm g, const Sched& S, const Epi& E, const PG8_LAS float* mid = nullptr) {
;     ...
;             if constexpr (SP2) {
;             PG8_LDB(B0, 0, 0); PG8_LDB(B1, 0, 1); PG8_SCHED; PG8_LDA(At, 0, 0); PG8_STAGE(PG8_SA(1, 1), a1 + hstepA, voffA);
;             PG8_WAIT_V(8); PG8_WAIT_L(0); PG8_BAR; PG8_MMA(0, 0, At, B0); PG8_MMA(0, 1, At, B1); PG8_BAR; PG8_SCHED;
;             PG8_LDA(At, 0, 1); PG8_STAGE(PG8_SB(0, 0), b2, voffB); PG8_STAGE(PG8_SB(0, 1), b2 + hstepB, voffB); PG8_STAGE(PG8_SA(0, 0), a2, voffA);
.LBB0_440:
	s_add_u32 s3, s14, s12
	s_addc_u32 s20, s15, s13
	s_add_u32 s3, s3, 0x100
	s_addc_u32 s20, s20, 0
	s_add_u32 s80, s71, s12
	s_addc_u32 s21, s78, s13
	s_add_i32 s81, 0, 0x10000
	s_cmpk_eq_i32 s12, 0x700
	s_cselect_b32 s53, s47, s20
	s_cselect_b32 s52, s69, s3
	v_add_u32_e32 v69, s81, v187
	s_cselect_b32 s21, s45, s21
	s_cselect_b32 s20, s70, s80
	s_add_i32 s3, 0, 0x14000
	ds_read_b128 v[70:73], v69
	ds_read_b128 v[74:77], v69 offset:1024
	ds_read_b128 v[148:151], v69 offset:2048
	ds_read_b128 v[152:155], v69 offset:3072
	v_add_u32_e32 v69, s3, v187
	ds_read_b128 v[180:183], v69
	ds_read_b128 v[194:197], v69 offset:1024
	ds_read_b128 v[198:201], v69 offset:2048
	ds_read_b128 v[202:205], v69 offset:3072
	v_lshl_add_u64 v[78:79], v[66:67], 0, s[12:13]
	s_add_i32 m0, s19, 0xc000
	ds_read_b128 v[220:223], v192
	ds_read_b128 v[224:227], v192 offset:1024
	ds_read_b128 v[228:231], v192 offset:2048
	ds_read_b128 v[232:235], v192 offset:3072
	ds_read_b128 v[236:239], v192 offset:4096
	ds_read_b128 v[240:243], v192 offset:5120
	ds_read_b128 v[244:247], v192 offset:6144
	ds_read_b128 v[248:251], v192 offset:7168
	global_load_lds_dwordx4 v[78:79], off
	v_lshl_add_u64 v[78:79], v[64:65], 0, s[12:13]
	s_add_i32 m0, s19, 0xe000
	s_nop 0
	global_load_lds_dwordx4 v[78:79], off
	s_waitcnt vmcnt(8)
	s_waitcnt lgkmcnt(0)
	s_barrier
	s_waitcnt lgkmcnt(0)
	v_mfma_f32_16x16x32_bf16 v[144:147], v[70:73], v[220:223], v[144:147]
	v_mfma_f32_16x16x32_bf16 v[140:143], v[148:151], v[220:223], v[140:143]
	v_mfma_f32_16x16x32_bf16 v[128:131], v[70:73], v[228:231], v[128:131]
	v_mfma_f32_16x16x32_bf16 v[124:127], v[148:151], v[228:231], v[124:127]
	v_mfma_f32_16x16x32_bf16 v[112:115], v[70:73], v[236:239], v[112:115]
	v_mfma_f32_16x16x32_bf16 v[108:111], v[148:151], v[236:239], v[108:111]
	v_mfma_f32_16x16x32_bf16 v[96:99], v[70:73], v[244:247], v[96:99]
	v_mfma_f32_16x16x32_bf16 v[92:95], v[148:151], v[244:247], v[92:95]
	v_mfma_f32_16x16x32_bf16 v[144:147], v[74:77], v[224:227], v[144:147]
	v_mfma_f32_16x16x32_bf16 v[140:143], v[152:155], v[224:227], v[140:143]
	v_mfma_f32_16x16x32_bf16 v[128:131], v[74:77], v[232:235], v[128:131]
	v_mfma_f32_16x16x32_bf16 v[124:127], v[152:155], v[232:235], v[124:127]
	v_mfma_f32_16x16x32_bf16 v[112:115], v[74:77], v[240:243], v[112:115]
	v_mfma_f32_16x16x32_bf16 v[108:111], v[152:155], v[240:243], v[108:111]
	v_mfma_f32_16x16x32_bf16 v[96:99], v[74:77], v[248:251], v[96:99]
	v_mfma_f32_16x16x32_bf16 v[92:95], v[152:155], v[248:251], v[92:95]
	v_mfma_f32_16x16x32_bf16 v[136:139], v[180:183], v[220:223], v[136:139]
	v_mfma_f32_16x16x32_bf16 v[132:135], v[198:201], v[220:223], v[132:135]
	v_mfma_f32_16x16x32_bf16 v[120:123], v[180:183], v[228:231], v[120:123]
	v_mfma_f32_16x16x32_bf16 v[116:119], v[198:201], v[228:231], v[116:119]
	v_mfma_f32_16x16x32_bf16 v[104:107], v[180:183], v[236:239], v[104:107]
	v_mfma_f32_16x16x32_bf16 v[100:103], v[198:201], v[236:239], v[100:103]
	v_mfma_f32_16x16x32_bf16 v[88:91], v[180:183], v[244:247], v[88:91]
	v_mfma_f32_16x16x32_bf16 v[82:85], v[198:201], v[244:247], v[84:87]
	v_mfma_f32_16x16x32_bf16 v[136:139], v[194:197], v[224:227], v[136:139]
	v_mfma_f32_16x16x32_bf16 v[132:135], v[202:205], v[224:227], v[132:135]
	v_mfma_f32_16x16x32_bf16 v[120:123], v[194:197], v[232:235], v[120:123]
	v_mfma_f32_16x16x32_bf16 v[116:119], v[202:205], v[232:235], v[116:119]
	v_mfma_f32_16x16x32_bf16 v[104:107], v[194:197], v[240:243], v[104:107]
	v_mfma_f32_16x16x32_bf16 v[100:103], v[202:205], v[240:243], v[100:103]
	v_mfma_f32_16x16x32_bf16 v[88:91], v[194:197], v[248:251], v[88:91]
	v_mfma_f32_16x16x32_bf16 v[82:85], v[202:205], v[248:251], v[82:85]
	s_barrier
	s_add_i32 s80, s81, s2
	v_lshl_add_u64 v[78:79], s[20:21], 0, v[158:159]
	s_mov_b32 m0, s80
	ds_read_b128 v[220:223], v192 offset:16384
	ds_read_b128 v[224:227], v192 offset:17408
	ds_read_b128 v[228:231], v192 offset:18432
	ds_read_b128 v[232:235], v192 offset:19456
	ds_read_b128 v[236:239], v192 offset:20480
	ds_read_b128 v[240:243], v192 offset:21504
	ds_read_b128 v[244:247], v192 offset:22528
	ds_read_b128 v[248:251], v192 offset:23552
	global_load_lds_dwordx4 v[78:79], off
	s_add_i32 m0, s80, 0x2000
	s_add_u32 s80, s20, 0x40000
	v_lshl_add_u64 v[184:185], s[20:21], 0, v[174:175]
	s_addc_u32 s81, s21, 0
	s_add_i32 s3, s3, s2
	global_load_lds_dwordx4 v[184:185], off
	v_lshl_add_u64 v[86:87], s[80:81], 0, v[158:159]
	s_mov_b32 m0, s3
	v_lshl_add_u64 v[252:253], s[52:53], 0, v[156:157]
	global_load_lds_dwordx4 v[86:87], off
	v_lshl_add_u64 v[86:87], s[80:81], 0, v[174:175]
	s_add_i32 m0, s3, 0x2000
	v_lshl_add_u64 v[210:211], s[52:53], 0, v[160:161]
	global_load_lds_dwordx4 v[86:87], off
	s_mov_b32 m0, s19
	s_nop 0
	global_load_lds_dwordx4 v[252:253], off
	s_mov_b32 m0, s54
	s_nop 0
	global_load_lds_dwordx4 v[210:211], off
	s_waitcnt vmcnt(8)
	s_waitcnt lgkmcnt(0)
	s_barrier
; #define PG8_STAGE(bufoff, gbase, voff) do { _Pragma("unroll") for (int _i = 0; _i < 2; ++_i) \
;         __builtin_amdgcn_global_load_lds((const unsigned*)((const char*)(gbase) + (voff)[_i]), (PG8_LAS unsigned*)(lds + (bufoff) + ldsw + _i * 8192), 16, 0, 0); } while (0)
; #define PG8_LDA(dst, b, h) do { _Pragma("unroll") for (int m = 0; m < 4; ++m) _Pragma("unroll") for (int k = 0; k < 2; ++k) dst[m][k] = *(const PG8_LAS bf16x8*)(lds + PG8_SA(b, h) + aoff + m * 2048 + k * 1024); } while (0)
; #define PG8_LDB(dst, b, h) do { _Pragma("unroll") for (int n = 0; n < 2; ++n) _Pragma("unroll") for (int k = 0; k < 2; ++k) dst[n][k] = *(const PG8_LAS bf16x8*)(lds + PG8_SB(b, h) + boff + n * 2048 + k * 1024); } while (0)
; #define PG8_MMA(ai, bj, At, Bt) do { __builtin_amdgcn_s_setprio(1); _Pragma("unroll") for (int m = 0; m < 4; ++m) _Pragma("unroll") for (int n = 0; n < 2; ++n) _Pragma("unroll") for (int k = 0; k < 2; ++k) \
;         acc[ai][bj][m][n] = __builtin_amdgcn_mfma_f32_16x16x32_bf16(Bt[n][k], At[m][k], acc[ai][bj][m][n], 0, 0, 0); __builtin_amdgcn_s_setprio(0); } while (0)
; #define PG8_WAIT_V(n) asm volatile("s_waitcnt vmcnt(" #n ")" ::: "memory")
; #define PG8_WAIT_L(n) asm volatile("s_waitcnt lgkmcnt(" #n ")" ::: "memory")
; #define PG8_BAR __builtin_amdgcn_s_barrier()
; #define PG8_SCHED __builtin_amdgcn_sched_barrier(0)
; template <class Epi, class Sched, bool ALIGN_EPI = false, bool SP2 = false, bool MID = false>
; __device__ __forceinline__ void gemm_phase(PG8_LAS unsigned char* lds, const Gemm g, const Sched& S, const Epi& E, const PG8_LAS float* mid = nullptr) {
;     ...
;             PG8_WAIT_V(8); PG8_WAIT_L(0); PG8_BAR; PG8_MMA(1, 0, At, B0); PG8_MMA(1, 1, At, B1); PG8_BAR; PG8_SCHED;
;             PG8_LDB(B0, 1, 0); PG8_LDB(B1, 1, 1); PG8_SCHED; PG8_LDA(At, 1, 0); PG8_STAGE(PG8_SA(0, 1), a2 + hstepA, voffA);
;             PG8_WAIT_V(8); PG8_WAIT_L(0); PG8_BAR; PG8_MMA(0, 0, At, B0); PG8_MMA(0, 1, At, B1); PG8_BAR; PG8_SCHED;
	s_waitcnt lgkmcnt(0)
	v_mfma_f32_16x16x32_bf16 v[60:63], v[70:73], v[220:223], v[60:63]
	v_mfma_f32_16x16x32_bf16 v[56:59], v[148:151], v[220:223], v[56:59]
	v_mfma_f32_16x16x32_bf16 v[44:47], v[70:73], v[228:231], v[44:47]
	v_mfma_f32_16x16x32_bf16 v[40:43], v[148:151], v[228:231], v[40:43]
	v_mfma_f32_16x16x32_bf16 v[28:31], v[70:73], v[236:239], v[28:31]
	v_mfma_f32_16x16x32_bf16 v[24:27], v[148:151], v[236:239], v[24:27]
	v_mfma_f32_16x16x32_bf16 v[12:15], v[70:73], v[244:247], v[12:15]
	v_mfma_f32_16x16x32_bf16 v[8:11], v[148:151], v[244:247], v[8:11]
	v_mfma_f32_16x16x32_bf16 v[60:63], v[74:77], v[224:227], v[60:63]
	v_mfma_f32_16x16x32_bf16 v[56:59], v[152:155], v[224:227], v[56:59]
	v_mfma_f32_16x16x32_bf16 v[44:47], v[74:77], v[232:235], v[44:47]
	v_mfma_f32_16x16x32_bf16 v[40:43], v[152:155], v[232:235], v[40:43]
	v_mfma_f32_16x16x32_bf16 v[28:31], v[74:77], v[240:243], v[28:31]
	v_mfma_f32_16x16x32_bf16 v[24:27], v[152:155], v[240:243], v[24:27]
	v_mfma_f32_16x16x32_bf16 v[12:15], v[74:77], v[248:251], v[12:15]
	v_mfma_f32_16x16x32_bf16 v[8:11], v[152:155], v[248:251], v[8:11]
	v_mfma_f32_16x16x32_bf16 v[52:55], v[180:183], v[220:223], v[52:55]
	v_mfma_f32_16x16x32_bf16 v[48:51], v[198:201], v[220:223], v[48:51]
	v_mfma_f32_16x16x32_bf16 v[36:39], v[180:183], v[228:231], v[36:39]
	v_mfma_f32_16x16x32_bf16 v[32:35], v[198:201], v[228:231], v[32:35]
	v_mfma_f32_16x16x32_bf16 v[20:23], v[180:183], v[236:239], v[20:23]
	v_mfma_f32_16x16x32_bf16 v[16:19], v[198:201], v[236:239], v[16:19]
	v_mfma_f32_16x16x32_bf16 v[4:7], v[180:183], v[244:247], v[4:7]
	v_mfma_f32_16x16x32_bf16 v[0:3], v[198:201], v[244:247], v[0:3]
	v_mfma_f32_16x16x32_bf16 v[52:55], v[194:197], v[224:227], v[52:55]
	v_mfma_f32_16x16x32_bf16 v[48:51], v[202:205], v[224:227], v[48:51]
	v_mfma_f32_16x16x32_bf16 v[36:39], v[194:197], v[232:235], v[36:39]
	v_mfma_f32_16x16x32_bf16 v[32:35], v[202:205], v[232:235], v[32:35]
	v_mfma_f32_16x16x32_bf16 v[20:23], v[194:197], v[240:243], v[20:23]
	v_mfma_f32_16x16x32_bf16 v[16:19], v[202:205], v[240:243], v[16:19]
	v_mfma_f32_16x16x32_bf16 v[4:7], v[194:197], v[248:251], v[4:7]
	v_mfma_f32_16x16x32_bf16 v[0:3], v[202:205], v[248:251], v[0:3]
	s_barrier
	s_add_i32 s3, 0, 0x18000
	v_add_u32_e32 v69, s3, v187
	s_add_i32 s80, 0, 0x1c000
	ds_read_b128 v[70:73], v69
	ds_read_b128 v[74:77], v69 offset:1024
	ds_read_b128 v[148:151], v69 offset:2048
	ds_read_b128 v[152:155], v69 offset:3072
	v_add_u32_e32 v69, s80, v187
	ds_read_b128 v[180:183], v69
	ds_read_b128 v[194:197], v69 offset:1024
	ds_read_b128 v[198:201], v69 offset:2048
	ds_read_b128 v[202:205], v69 offset:3072
	s_add_u32 s52, s52, 0x40000
	s_addc_u32 s53, s53, 0
	s_mov_b32 m0, s55
	v_lshl_add_u64 v[86:87], s[52:53], 0, v[156:157]
	ds_read_b128 v[220:223], v192 offset:32768
	ds_read_b128 v[224:227], v192 offset:33792
	ds_read_b128 v[228:231], v192 offset:34816
	ds_read_b128 v[232:235], v192 offset:35840
	ds_read_b128 v[236:239], v192 offset:36864
	ds_read_b128 v[240:243], v192 offset:37888
	ds_read_b128 v[244:247], v192 offset:38912
	ds_read_b128 v[248:251], v192 offset:39936
	global_load_lds_dwordx4 v[86:87], off
	v_lshl_add_u64 v[86:87], s[52:53], 0, v[160:161]
	s_mov_b32 m0, s66
	s_nop 0
	global_load_lds_dwordx4 v[86:87], off
	s_waitcnt vmcnt(8)
	s_waitcnt lgkmcnt(0)
	s_barrier
	s_waitcnt lgkmcnt(0)
	v_mfma_f32_16x16x32_bf16 v[144:147], v[70:73], v[220:223], v[144:147]
	v_mfma_f32_16x16x32_bf16 v[140:143], v[148:151], v[220:223], v[140:143]
	v_mfma_f32_16x16x32_bf16 v[128:131], v[70:73], v[228:231], v[128:131]
	v_mfma_f32_16x16x32_bf16 v[124:127], v[148:151], v[228:231], v[124:127]
	v_mfma_f32_16x16x32_bf16 v[112:115], v[70:73], v[236:239], v[112:115]
	v_mfma_f32_16x16x32_bf16 v[108:111], v[148:151], v[236:239], v[108:111]
	v_mfma_f32_16x16x32_bf16 v[96:99], v[70:73], v[244:247], v[96:99]
	v_mfma_f32_16x16x32_bf16 v[92:95], v[148:151], v[244:247], v[92:95]
	v_mfma_f32_16x16x32_bf16 v[144:147], v[74:77], v[224:227], v[144:147]
	v_mfma_f32_16x16x32_bf16 v[140:143], v[152:155], v[224:227], v[140:143]
	v_mfma_f32_16x16x32_bf16 v[128:131], v[74:77], v[232:235], v[128:131]
	v_mfma_f32_16x16x32_bf16 v[124:127], v[152:155], v[232:235], v[124:127]
	v_mfma_f32_16x16x32_bf16 v[112:115], v[74:77], v[240:243], v[112:115]
	v_mfma_f32_16x16x32_bf16 v[108:111], v[152:155], v[240:243], v[108:111]
	v_mfma_f32_16x16x32_bf16 v[96:99], v[74:77], v[248:251], v[96:99]
	v_mfma_f32_16x16x32_bf16 v[92:95], v[152:155], v[248:251], v[92:95]
	v_mfma_f32_16x16x32_bf16 v[136:139], v[180:183], v[220:223], v[136:139]
	v_mfma_f32_16x16x32_bf16 v[132:135], v[198:201], v[220:223], v[132:135]
	v_mfma_f32_16x16x32_bf16 v[120:123], v[180:183], v[228:231], v[120:123]
	v_mfma_f32_16x16x32_bf16 v[116:119], v[198:201], v[228:231], v[116:119]
	v_mfma_f32_16x16x32_bf16 v[104:107], v[180:183], v[236:239], v[104:107]
	v_mfma_f32_16x16x32_bf16 v[100:103], v[198:201], v[236:239], v[100:103]
	v_mfma_f32_16x16x32_bf16 v[86:89], v[180:183], v[244:247], v[88:91]
	v_mfma_f32_16x16x32_bf16 v[82:85], v[198:201], v[244:247], v[82:85]
	v_mfma_f32_16x16x32_bf16 v[136:139], v[194:197], v[224:227], v[136:139]
	v_mfma_f32_16x16x32_bf16 v[132:135], v[202:205], v[224:227], v[132:135]
	v_mfma_f32_16x16x32_bf16 v[120:123], v[194:197], v[232:235], v[120:123]
	v_mfma_f32_16x16x32_bf16 v[116:119], v[202:205], v[232:235], v[116:119]
	v_mfma_f32_16x16x32_bf16 v[104:107], v[194:197], v[240:243], v[104:107]
	v_mfma_f32_16x16x32_bf16 v[100:103], v[202:205], v[240:243], v[100:103]
	v_mfma_f32_16x16x32_bf16 v[88:91], v[194:197], v[248:251], v[86:89]
	v_mfma_f32_16x16x32_bf16 v[84:87], v[202:205], v[248:251], v[82:85]
	s_barrier
; #define PG8_STAGE(bufoff, gbase, voff) do { _Pragma("unroll") for (int _i = 0; _i < 2; ++_i) \
;         __builtin_amdgcn_global_load_lds((const unsigned*)((const char*)(gbase) + (voff)[_i]), (PG8_LAS unsigned*)(lds + (bufoff) + ldsw + _i * 8192), 16, 0, 0); } while (0)
; #define PG8_LDA(dst, b, h) do { _Pragma("unroll") for (int m = 0; m < 4; ++m) _Pragma("unroll") for (int k = 0; k < 2; ++k) dst[m][k] = *(const PG8_LAS bf16x8*)(lds + PG8_SA(b, h) + aoff + m * 2048 + k * 1024); } while (0)
; #define PG8_MMA(ai, bj, At, Bt) do { __builtin_amdgcn_s_setprio(1); _Pragma("unroll") for (int m = 0; m < 4; ++m) _Pragma("unroll") for (int n = 0; n < 2; ++n) _Pragma("unroll") for (int k = 0; k < 2; ++k) \
;         acc[ai][bj][m][n] = __builtin_amdgcn_mfma_f32_16x16x32_bf16(Bt[n][k], At[m][k], acc[ai][bj][m][n], 0, 0, 0); __builtin_amdgcn_s_setprio(0); } while (0)
; #define PG8_WAIT_V(n) asm volatile("s_waitcnt vmcnt(" #n ")" ::: "memory")
; #define PG8_WAIT_L(n) asm volatile("s_waitcnt lgkmcnt(" #n ")" ::: "memory")
; #define PG8_BAR __builtin_amdgcn_s_barrier()
; #define PG8_SCHED __builtin_amdgcn_sched_barrier(0)
; template <class Epi, class Sched, bool ALIGN_EPI = false, bool SP2 = false, bool MID = false>
; __device__ __forceinline__ void gemm_phase(PG8_LAS unsigned char* lds, const Gemm g, const Sched& S, const Epi& E, const PG8_LAS float* mid = nullptr) {
;     ...
;         for (int t = 0; t < nt; t += 2) {
;     ...
;             PG8_LDA(At, 1, 1); PG8_STAGE(PG8_SB(1, 0), b3, voffB); PG8_STAGE(PG8_SB(1, 1), b3 + hstepB, voffB); PG8_STAGE(PG8_SA(1, 0), a3, voffA);
;             PG8_WAIT_V(8); PG8_WAIT_L(0); PG8_BAR; PG8_MMA(1, 0, At, B0); PG8_MMA(1, 1, At, B1); PG8_BAR; PG8_SCHED;
	s_add_i32 s3, s3, s2
	v_lshl_add_u64 v[78:79], v[78:79], 0, s[16:17]
	s_mov_b32 m0, s3
	ds_read_b128 v[220:223], v192 offset:49152
	ds_read_b128 v[224:227], v192 offset:50176
	ds_read_b128 v[228:231], v192 offset:51200
	ds_read_b128 v[232:235], v192 offset:52224
	ds_read_b128 v[236:239], v192 offset:53248
	ds_read_b128 v[240:243], v192 offset:54272
	ds_read_b128 v[244:247], v192 offset:55296
	ds_read_b128 v[248:251], v192 offset:56320
	global_load_lds_dwordx4 v[78:79], off
	s_add_i32 m0, s3, 0x2000
	s_add_u32 s20, s20, 0x40080
	v_lshl_add_u64 v[78:79], v[184:185], 0, s[16:17]
	s_addc_u32 s21, s21, 0
	s_add_i32 s3, s80, s2
	global_load_lds_dwordx4 v[78:79], off
	v_lshl_add_u64 v[78:79], s[20:21], 0, v[158:159]
	s_mov_b32 m0, s3
	s_nop 0
	global_load_lds_dwordx4 v[78:79], off
	v_lshl_add_u64 v[78:79], s[20:21], 0, v[174:175]
	s_add_i32 m0, s3, 0x2000
	s_nop 0
	global_load_lds_dwordx4 v[78:79], off
	v_lshl_add_u64 v[78:79], v[252:253], 0, s[16:17]
	s_mov_b32 m0, s10
	s_nop 0
	global_load_lds_dwordx4 v[78:79], off
	v_lshl_add_u64 v[78:79], v[210:211], 0, s[16:17]
	s_mov_b32 m0, s67
	s_nop 0
	global_load_lds_dwordx4 v[78:79], off
	s_waitcnt vmcnt(8)
	s_waitcnt lgkmcnt(0)
	s_barrier
	s_waitcnt lgkmcnt(0)
	v_mfma_f32_16x16x32_bf16 v[60:63], v[70:73], v[220:223], v[60:63]
	v_mfma_f32_16x16x32_bf16 v[56:59], v[148:151], v[220:223], v[56:59]
	v_mfma_f32_16x16x32_bf16 v[44:47], v[70:73], v[228:231], v[44:47]
	v_mfma_f32_16x16x32_bf16 v[40:43], v[148:151], v[228:231], v[40:43]
	v_mfma_f32_16x16x32_bf16 v[28:31], v[70:73], v[236:239], v[28:31]
	v_mfma_f32_16x16x32_bf16 v[24:27], v[148:151], v[236:239], v[24:27]
	v_mfma_f32_16x16x32_bf16 v[12:15], v[70:73], v[244:247], v[12:15]
	v_mfma_f32_16x16x32_bf16 v[8:11], v[148:151], v[244:247], v[8:11]
	v_mfma_f32_16x16x32_bf16 v[60:63], v[74:77], v[224:227], v[60:63]
	v_mfma_f32_16x16x32_bf16 v[56:59], v[152:155], v[224:227], v[56:59]
	v_mfma_f32_16x16x32_bf16 v[44:47], v[74:77], v[232:235], v[44:47]
	v_mfma_f32_16x16x32_bf16 v[40:43], v[152:155], v[232:235], v[40:43]
	v_mfma_f32_16x16x32_bf16 v[28:31], v[74:77], v[240:243], v[28:31]
	v_mfma_f32_16x16x32_bf16 v[24:27], v[152:155], v[240:243], v[24:27]
	v_mfma_f32_16x16x32_bf16 v[12:15], v[74:77], v[248:251], v[12:15]
	v_mfma_f32_16x16x32_bf16 v[8:11], v[152:155], v[248:251], v[8:11]
	v_mfma_f32_16x16x32_bf16 v[52:55], v[180:183], v[220:223], v[52:55]
	v_mfma_f32_16x16x32_bf16 v[48:51], v[198:201], v[220:223], v[48:51]
	v_mfma_f32_16x16x32_bf16 v[36:39], v[180:183], v[228:231], v[36:39]
	v_mfma_f32_16x16x32_bf16 v[32:35], v[198:201], v[228:231], v[32:35]
	v_mfma_f32_16x16x32_bf16 v[20:23], v[180:183], v[236:239], v[20:23]
	v_mfma_f32_16x16x32_bf16 v[16:19], v[198:201], v[236:239], v[16:19]
	v_mfma_f32_16x16x32_bf16 v[4:7], v[180:183], v[244:247], v[4:7]
	v_mfma_f32_16x16x32_bf16 v[0:3], v[198:201], v[244:247], v[0:3]
	v_mfma_f32_16x16x32_bf16 v[52:55], v[194:197], v[224:227], v[52:55]
	v_mfma_f32_16x16x32_bf16 v[48:51], v[202:205], v[224:227], v[48:51]
	v_mfma_f32_16x16x32_bf16 v[36:39], v[194:197], v[232:235], v[36:39]
	v_mfma_f32_16x16x32_bf16 v[32:35], v[202:205], v[232:235], v[32:35]
	v_mfma_f32_16x16x32_bf16 v[20:23], v[194:197], v[240:243], v[20:23]
	v_mfma_f32_16x16x32_bf16 v[16:19], v[202:205], v[240:243], v[16:19]
	v_mfma_f32_16x16x32_bf16 v[4:7], v[194:197], v[248:251], v[4:7]
	v_mfma_f32_16x16x32_bf16 v[0:3], v[202:205], v[248:251], v[0:3]
	s_barrier
	s_add_i32 s79, s79, 2
	s_add_u32 s12, s12, 0x100
	s_addc_u32 s13, s13, 0
	s_cmp_gt_u32 s79, 13
	s_cbranch_scc1 .LBB0_443

; #define PG8_STAGE(bufoff, gbase, voff) do { _Pragma("unroll") for (int _i = 0; _i < 2; ++_i) \
;         __builtin_amdgcn_global_load_lds((const unsigned*)((const char*)(gbase) + (voff)[_i]), (PG8_LAS unsigned*)(lds + (bufoff) + ldsw + _i * 8192), 16, 0, 0); } while (0)
; #define PG8_LDA(dst, b, h) do { _Pragma("unroll") for (int m = 0; m < 4; ++m) _Pragma("unroll") for (int k = 0; k < 2; ++k) dst[m][k] = *(const PG8_LAS bf16x8*)(lds + PG8_SA(b, h) + aoff + m * 2048 + k * 1024); } while (0)
; #define PG8_LDB(dst, b, h) do { _Pragma("unroll") for (int n = 0; n < 2; ++n) _Pragma("unroll") for (int k = 0; k < 2; ++k) dst[n][k] = *(const PG8_LAS bf16x8*)(lds + PG8_SB(b, h) + boff + n * 2048 + k * 1024); } while (0)
; #define PG8_MMA(ai, bj, At, Bt) do { __builtin_amdgcn_s_setprio(1); _Pragma("unroll") for (int m = 0; m < 4; ++m) _Pragma("unroll") for (int n = 0; n < 2; ++n) _Pragma("unroll") for (int k = 0; k < 2; ++k) \
;         acc[ai][bj][m][n] = __builtin_amdgcn_mfma_f32_16x16x32_bf16(Bt[n][k], At[m][k], acc[ai][bj][m][n], 0, 0, 0); __builtin_amdgcn_s_setprio(0); } while (0)
; #define PG8_WAIT_V(n) asm volatile("s_waitcnt vmcnt(" #n ")" ::: "memory")
; #define PG8_WAIT_L(n) asm volatile("s_waitcnt lgkmcnt(" #n ")" ::: "memory")
; #define PG8_BAR __builtin_amdgcn_s_barrier()
; #define PG8_SCHED __builtin_amdgcn_sched_barrier(0)
; template <class Epi, class Sched, bool ALIGN_EPI = false, bool SP2 = false, bool MID = false>
; __device__ __forceinline__ void gemm_phase(PG8_LAS unsigned char* lds, const Gemm g, const Sched& S, const Epi& E, const PG8_LAS float* mid = nullptr) {
;     ...
;             if constexpr (SP2) {
;             PG8_LDB(B0, 0, 0); PG8_LDB(B1, 0, 1); PG8_SCHED; PG8_LDA(At, 0, 0); PG8_STAGE(PG8_SA(1, 1), a1 + hstepA, voffA);
;             PG8_WAIT_V(8); PG8_WAIT_L(0); PG8_BAR; PG8_MMA(0, 0, At, B0); PG8_MMA(0, 1, At, B1); PG8_BAR; PG8_SCHED;
;             PG8_LDA(At, 0, 1); PG8_STAGE(PG8_SB(0, 0), b2, voffB); PG8_STAGE(PG8_SB(0, 1), b2 + hstepB, voffB); PG8_STAGE(PG8_SA(0, 0), a2, voffA);
.LBB0_559:
	s_add_u32 s3, s12, 0xfffc0080
	s_addc_u32 s38, s13, -1
	s_add_i32 s71, 0, 0x10000
	s_cmp_eq_u32 s70, 12
	s_cselect_b32 s41, s5, s38
	s_cselect_b32 s40, s21, s3
	v_add_u32_e32 v80, s71, v220
	s_cselect_b32 s39, s42, s65
	s_cselect_b32 s38, s43, s63
	s_add_i32 s3, 0, 0x14000
	ds_read_b128 v[130:133], v80
	ds_read_b128 v[134:137], v80 offset:1024
	ds_read_b128 v[138:141], v80 offset:2048
	ds_read_b128 v[142:145], v80 offset:3072
	v_add_u32_e32 v80, s3, v220
	ds_read_b128 v[146:149], v80
	ds_read_b128 v[150:153], v80 offset:1024
	ds_read_b128 v[154:157], v80 offset:2048
	ds_read_b128 v[158:161], v80 offset:3072
	v_lshl_add_u64 v[204:205], s[12:13], 0, v[182:183]
	s_add_i32 m0, s19, 0xc000
	ds_read_b128 v[188:191], v221
	ds_read_b128 v[192:195], v221 offset:1024
	ds_read_b128 v[196:199], v221 offset:2048
	ds_read_b128 v[200:203], v221 offset:3072
	ds_read_b128 v[222:225], v221 offset:4096
	ds_read_b128 v[226:229], v221 offset:5120
	ds_read_b128 v[230:233], v221 offset:6144
	ds_read_b128 v[234:237], v221 offset:7168
	global_load_lds_dwordx4 v[204:205], off
	v_lshl_add_u64 v[204:205], s[12:13], 0, v[184:185]
	s_add_i32 m0, s19, 0xe000
	s_nop 0
	global_load_lds_dwordx4 v[204:205], off
	s_waitcnt vmcnt(8)
	s_waitcnt lgkmcnt(0)
	s_barrier
	s_waitcnt lgkmcnt(0)
	v_mfma_f32_16x16x32_bf16 v[126:129], v[130:133], v[188:191], v[126:129]
	v_mfma_f32_16x16x32_bf16 v[94:97], v[138:141], v[188:191], v[94:97]
	v_mfma_f32_16x16x32_bf16 v[118:121], v[130:133], v[196:199], v[118:121]
	v_mfma_f32_16x16x32_bf16 v[86:89], v[138:141], v[196:199], v[86:89]
	v_mfma_f32_16x16x32_bf16 v[110:113], v[130:133], v[222:225], v[110:113]
	v_mfma_f32_16x16x32_bf16 v[76:79], v[138:141], v[222:225], v[76:79]
	v_mfma_f32_16x16x32_bf16 v[102:105], v[130:133], v[230:233], v[102:105]
	v_mfma_f32_16x16x32_bf16 v[68:71], v[138:141], v[230:233], v[68:71]
	v_mfma_f32_16x16x32_bf16 v[126:129], v[134:137], v[192:195], v[126:129]
	v_mfma_f32_16x16x32_bf16 v[94:97], v[142:145], v[192:195], v[94:97]
	v_mfma_f32_16x16x32_bf16 v[118:121], v[134:137], v[200:203], v[118:121]
	v_mfma_f32_16x16x32_bf16 v[86:89], v[142:145], v[200:203], v[86:89]
	v_mfma_f32_16x16x32_bf16 v[110:113], v[134:137], v[226:229], v[110:113]
	v_mfma_f32_16x16x32_bf16 v[76:79], v[142:145], v[226:229], v[76:79]
	v_mfma_f32_16x16x32_bf16 v[102:105], v[134:137], v[234:237], v[102:105]
	v_mfma_f32_16x16x32_bf16 v[68:71], v[142:145], v[234:237], v[68:71]
	v_mfma_f32_16x16x32_bf16 v[122:125], v[146:149], v[188:191], v[122:125]
	v_mfma_f32_16x16x32_bf16 v[90:93], v[154:157], v[188:191], v[90:93]
	v_mfma_f32_16x16x32_bf16 v[114:117], v[146:149], v[196:199], v[114:117]
	v_mfma_f32_16x16x32_bf16 v[82:85], v[154:157], v[196:199], v[82:85]
	v_mfma_f32_16x16x32_bf16 v[106:109], v[146:149], v[222:225], v[106:109]
	v_mfma_f32_16x16x32_bf16 v[72:75], v[154:157], v[222:225], v[72:75]
	v_mfma_f32_16x16x32_bf16 v[98:101], v[146:149], v[230:233], v[98:101]
	v_mfma_f32_16x16x32_bf16 v[64:67], v[154:157], v[230:233], v[64:67]
	v_mfma_f32_16x16x32_bf16 v[122:125], v[150:153], v[192:195], v[122:125]
	v_mfma_f32_16x16x32_bf16 v[90:93], v[158:161], v[192:195], v[90:93]
	v_mfma_f32_16x16x32_bf16 v[114:117], v[150:153], v[200:203], v[114:117]
	v_mfma_f32_16x16x32_bf16 v[82:85], v[158:161], v[200:203], v[82:85]
	v_mfma_f32_16x16x32_bf16 v[106:109], v[150:153], v[226:229], v[106:109]
	v_mfma_f32_16x16x32_bf16 v[72:75], v[158:161], v[226:229], v[72:75]
	v_mfma_f32_16x16x32_bf16 v[98:101], v[150:153], v[234:237], v[98:101]
	v_mfma_f32_16x16x32_bf16 v[64:67], v[158:161], v[234:237], v[64:67]
	s_barrier
	s_add_i32 s71, s71, s85
	v_lshl_add_u64 v[204:205], s[38:39], 0, v[176:177]
	s_mov_b32 m0, s71
	ds_read_b128 v[188:191], v221 offset:16384
	ds_read_b128 v[192:195], v221 offset:17408
	ds_read_b128 v[196:199], v221 offset:18432
	ds_read_b128 v[200:203], v221 offset:19456
	ds_read_b128 v[222:225], v221 offset:20480
	ds_read_b128 v[226:229], v221 offset:21504
	ds_read_b128 v[230:233], v221 offset:22528
	ds_read_b128 v[234:237], v221 offset:23552
	global_load_lds_dwordx4 v[204:205], off
	s_add_i32 m0, s71, 0x2000
	s_add_u32 s80, s38, 0x40000
	v_lshl_add_u64 v[210:211], s[38:39], 0, v[180:181]
	s_addc_u32 s81, s39, 0
	s_add_i32 s3, s3, s85
	global_load_lds_dwordx4 v[210:211], off
	v_lshl_add_u64 v[212:213], s[80:81], 0, v[176:177]
	s_mov_b32 m0, s3
	v_lshl_add_u64 v[238:239], s[40:41], 0, v[178:179]
	global_load_lds_dwordx4 v[212:213], off
	v_lshl_add_u64 v[212:213], s[80:81], 0, v[180:181]
	s_add_i32 m0, s3, 0x2000
	s_nop 0
	global_load_lds_dwordx4 v[212:213], off
	v_lshl_add_u64 v[212:213], s[40:41], 0, v[174:175]
	s_mov_b32 m0, s19
	s_nop 0
	global_load_lds_dwordx4 v[212:213], off
	s_mov_b32 m0, s46
	s_nop 0
	global_load_lds_dwordx4 v[238:239], off
	s_waitcnt vmcnt(8)
	s_waitcnt lgkmcnt(0)
	s_barrier
; #define PG8_STAGE(bufoff, gbase, voff) do { _Pragma("unroll") for (int _i = 0; _i < 2; ++_i) \
;         __builtin_amdgcn_global_load_lds((const unsigned*)((const char*)(gbase) + (voff)[_i]), (PG8_LAS unsigned*)(lds + (bufoff) + ldsw + _i * 8192), 16, 0, 0); } while (0)
; #define PG8_LDA(dst, b, h) do { _Pragma("unroll") for (int m = 0; m < 4; ++m) _Pragma("unroll") for (int k = 0; k < 2; ++k) dst[m][k] = *(const PG8_LAS bf16x8*)(lds + PG8_SA(b, h) + aoff + m * 2048 + k * 1024); } while (0)
; #define PG8_LDB(dst, b, h) do { _Pragma("unroll") for (int n = 0; n < 2; ++n) _Pragma("unroll") for (int k = 0; k < 2; ++k) dst[n][k] = *(const PG8_LAS bf16x8*)(lds + PG8_SB(b, h) + boff + n * 2048 + k * 1024); } while (0)
; #define PG8_MMA(ai, bj, At, Bt) do { __builtin_amdgcn_s_setprio(1); _Pragma("unroll") for (int m = 0; m < 4; ++m) _Pragma("unroll") for (int n = 0; n < 2; ++n) _Pragma("unroll") for (int k = 0; k < 2; ++k) \
;         acc[ai][bj][m][n] = __builtin_amdgcn_mfma_f32_16x16x32_bf16(Bt[n][k], At[m][k], acc[ai][bj][m][n], 0, 0, 0); __builtin_amdgcn_s_setprio(0); } while (0)
; #define PG8_WAIT_V(n) asm volatile("s_waitcnt vmcnt(" #n ")" ::: "memory")
; #define PG8_WAIT_L(n) asm volatile("s_waitcnt lgkmcnt(" #n ")" ::: "memory")
; #define PG8_BAR __builtin_amdgcn_s_barrier()
; #define PG8_SCHED __builtin_amdgcn_sched_barrier(0)
; template <class Epi, class Sched, bool ALIGN_EPI = false, bool SP2 = false, bool MID = false>
; __device__ __forceinline__ void gemm_phase(PG8_LAS unsigned char* lds, const Gemm g, const Sched& S, const Epi& E, const PG8_LAS float* mid = nullptr) {
;     ...
;             PG8_WAIT_V(8); PG8_WAIT_L(0); PG8_BAR; PG8_MMA(1, 0, At, B0); PG8_MMA(1, 1, At, B1); PG8_BAR; PG8_SCHED;
;             PG8_LDB(B0, 1, 0); PG8_LDB(B1, 1, 1); PG8_SCHED; PG8_LDA(At, 1, 0); PG8_STAGE(PG8_SA(0, 1), a2 + hstepA, voffA);
;             PG8_WAIT_V(8); PG8_WAIT_L(0); PG8_BAR; PG8_MMA(0, 0, At, B0); PG8_MMA(0, 1, At, B1); PG8_BAR; PG8_SCHED;
	s_waitcnt lgkmcnt(0)
	v_mfma_f32_16x16x32_bf16 v[60:63], v[130:133], v[188:191], v[60:63]
	v_mfma_f32_16x16x32_bf16 v[28:31], v[138:141], v[188:191], v[28:31]
	v_mfma_f32_16x16x32_bf16 v[52:55], v[130:133], v[196:199], v[52:55]
	v_mfma_f32_16x16x32_bf16 v[20:23], v[138:141], v[196:199], v[20:23]
	v_mfma_f32_16x16x32_bf16 v[44:47], v[130:133], v[222:225], v[44:47]
	v_mfma_f32_16x16x32_bf16 v[12:15], v[138:141], v[222:225], v[12:15]
	v_mfma_f32_16x16x32_bf16 v[36:39], v[130:133], v[230:233], v[36:39]
	v_mfma_f32_16x16x32_bf16 v[4:7], v[138:141], v[230:233], v[4:7]
	v_mfma_f32_16x16x32_bf16 v[60:63], v[134:137], v[192:195], v[60:63]
	v_mfma_f32_16x16x32_bf16 v[28:31], v[142:145], v[192:195], v[28:31]
	v_mfma_f32_16x16x32_bf16 v[52:55], v[134:137], v[200:203], v[52:55]
	v_mfma_f32_16x16x32_bf16 v[20:23], v[142:145], v[200:203], v[20:23]
	v_mfma_f32_16x16x32_bf16 v[44:47], v[134:137], v[226:229], v[44:47]
	v_mfma_f32_16x16x32_bf16 v[12:15], v[142:145], v[226:229], v[12:15]
	v_mfma_f32_16x16x32_bf16 v[36:39], v[134:137], v[234:237], v[36:39]
	v_mfma_f32_16x16x32_bf16 v[4:7], v[142:145], v[234:237], v[4:7]
	v_mfma_f32_16x16x32_bf16 v[56:59], v[146:149], v[188:191], v[56:59]
	v_mfma_f32_16x16x32_bf16 v[24:27], v[154:157], v[188:191], v[24:27]
	v_mfma_f32_16x16x32_bf16 v[48:51], v[146:149], v[196:199], v[48:51]
	v_mfma_f32_16x16x32_bf16 v[16:19], v[154:157], v[196:199], v[16:19]
	v_mfma_f32_16x16x32_bf16 v[40:43], v[146:149], v[222:225], v[40:43]
	v_mfma_f32_16x16x32_bf16 v[8:11], v[154:157], v[222:225], v[8:11]
	v_mfma_f32_16x16x32_bf16 v[32:35], v[146:149], v[230:233], v[32:35]
	v_mfma_f32_16x16x32_bf16 v[0:3], v[154:157], v[230:233], v[0:3]
	v_mfma_f32_16x16x32_bf16 v[56:59], v[150:153], v[192:195], v[56:59]
	v_mfma_f32_16x16x32_bf16 v[24:27], v[158:161], v[192:195], v[24:27]
	v_mfma_f32_16x16x32_bf16 v[48:51], v[150:153], v[200:203], v[48:51]
	v_mfma_f32_16x16x32_bf16 v[16:19], v[158:161], v[200:203], v[16:19]
	v_mfma_f32_16x16x32_bf16 v[40:43], v[150:153], v[226:229], v[40:43]
	v_mfma_f32_16x16x32_bf16 v[8:11], v[158:161], v[226:229], v[8:11]
	v_mfma_f32_16x16x32_bf16 v[32:35], v[150:153], v[234:237], v[32:35]
	v_mfma_f32_16x16x32_bf16 v[0:3], v[158:161], v[234:237], v[0:3]
	s_barrier
	s_add_i32 s3, 0, 0x18000
	v_add_u32_e32 v80, s3, v220
	s_add_i32 s71, 0, 0x1c000
	ds_read_b128 v[130:133], v80
	ds_read_b128 v[134:137], v80 offset:1024
	ds_read_b128 v[138:141], v80 offset:2048
	ds_read_b128 v[142:145], v80 offset:3072
	v_add_u32_e32 v80, s71, v220
	ds_read_b128 v[146:149], v80
	ds_read_b128 v[150:153], v80 offset:1024
	ds_read_b128 v[154:157], v80 offset:2048
	ds_read_b128 v[158:161], v80 offset:3072
	s_add_u32 s40, s40, 0x40000
	s_addc_u32 s41, s41, 0
	s_mov_b32 m0, s47
	v_lshl_add_u64 v[240:241], s[40:41], 0, v[174:175]
	ds_read_b128 v[188:191], v221 offset:32768
	ds_read_b128 v[192:195], v221 offset:33792
	ds_read_b128 v[196:199], v221 offset:34816
	ds_read_b128 v[200:203], v221 offset:35840
	ds_read_b128 v[222:225], v221 offset:36864
	ds_read_b128 v[226:229], v221 offset:37888
	ds_read_b128 v[230:233], v221 offset:38912
	ds_read_b128 v[234:237], v221 offset:39936
	global_load_lds_dwordx4 v[240:241], off
	v_lshl_add_u64 v[240:241], s[40:41], 0, v[178:179]
	s_mov_b32 m0, s2
	s_nop 0
	global_load_lds_dwordx4 v[240:241], off
	s_waitcnt vmcnt(8)
	s_waitcnt lgkmcnt(0)
	s_barrier
	s_waitcnt lgkmcnt(0)
	v_mfma_f32_16x16x32_bf16 v[126:129], v[130:133], v[188:191], v[126:129]
	v_mfma_f32_16x16x32_bf16 v[94:97], v[138:141], v[188:191], v[94:97]
	v_mfma_f32_16x16x32_bf16 v[118:121], v[130:133], v[196:199], v[118:121]
	v_mfma_f32_16x16x32_bf16 v[86:89], v[138:141], v[196:199], v[86:89]
	v_mfma_f32_16x16x32_bf16 v[110:113], v[130:133], v[222:225], v[110:113]
	v_mfma_f32_16x16x32_bf16 v[76:79], v[138:141], v[222:225], v[76:79]
	v_mfma_f32_16x16x32_bf16 v[102:105], v[130:133], v[230:233], v[102:105]
	v_mfma_f32_16x16x32_bf16 v[68:71], v[138:141], v[230:233], v[68:71]
	v_mfma_f32_16x16x32_bf16 v[126:129], v[134:137], v[192:195], v[126:129]
	v_mfma_f32_16x16x32_bf16 v[94:97], v[142:145], v[192:195], v[94:97]
	v_mfma_f32_16x16x32_bf16 v[118:121], v[134:137], v[200:203], v[118:121]
	v_mfma_f32_16x16x32_bf16 v[86:89], v[142:145], v[200:203], v[86:89]
	v_mfma_f32_16x16x32_bf16 v[110:113], v[134:137], v[226:229], v[110:113]
	v_mfma_f32_16x16x32_bf16 v[76:79], v[142:145], v[226:229], v[76:79]
	v_mfma_f32_16x16x32_bf16 v[102:105], v[134:137], v[234:237], v[102:105]
	v_mfma_f32_16x16x32_bf16 v[68:71], v[142:145], v[234:237], v[68:71]
	v_mfma_f32_16x16x32_bf16 v[122:125], v[146:149], v[188:191], v[122:125]
	v_mfma_f32_16x16x32_bf16 v[90:93], v[154:157], v[188:191], v[90:93]
	v_mfma_f32_16x16x32_bf16 v[114:117], v[146:149], v[196:199], v[114:117]
	v_mfma_f32_16x16x32_bf16 v[82:85], v[154:157], v[196:199], v[82:85]
	v_mfma_f32_16x16x32_bf16 v[106:109], v[146:149], v[222:225], v[106:109]
	v_mfma_f32_16x16x32_bf16 v[72:75], v[154:157], v[222:225], v[72:75]
	v_mfma_f32_16x16x32_bf16 v[98:101], v[146:149], v[230:233], v[98:101]
	v_mfma_f32_16x16x32_bf16 v[64:67], v[154:157], v[230:233], v[64:67]
	v_mfma_f32_16x16x32_bf16 v[122:125], v[150:153], v[192:195], v[122:125]
	v_mfma_f32_16x16x32_bf16 v[90:93], v[158:161], v[192:195], v[90:93]
	v_mfma_f32_16x16x32_bf16 v[114:117], v[150:153], v[200:203], v[114:117]
	v_mfma_f32_16x16x32_bf16 v[82:85], v[158:161], v[200:203], v[82:85]
	v_mfma_f32_16x16x32_bf16 v[106:109], v[150:153], v[226:229], v[106:109]
	v_mfma_f32_16x16x32_bf16 v[72:75], v[158:161], v[226:229], v[72:75]
	v_mfma_f32_16x16x32_bf16 v[98:101], v[150:153], v[234:237], v[98:101]
	v_mfma_f32_16x16x32_bf16 v[64:67], v[158:161], v[234:237], v[64:67]
	s_barrier
; #define PG8_STAGE(bufoff, gbase, voff) do { _Pragma("unroll") for (int _i = 0; _i < 2; ++_i) \
;         __builtin_amdgcn_global_load_lds((const unsigned*)((const char*)(gbase) + (voff)[_i]), (PG8_LAS unsigned*)(lds + (bufoff) + ldsw + _i * 8192), 16, 0, 0); } while (0)
; #define PG8_LDA(dst, b, h) do { _Pragma("unroll") for (int m = 0; m < 4; ++m) _Pragma("unroll") for (int k = 0; k < 2; ++k) dst[m][k] = *(const PG8_LAS bf16x8*)(lds + PG8_SA(b, h) + aoff + m * 2048 + k * 1024); } while (0)
; #define PG8_MMA(ai, bj, At, Bt) do { __builtin_amdgcn_s_setprio(1); _Pragma("unroll") for (int m = 0; m < 4; ++m) _Pragma("unroll") for (int n = 0; n < 2; ++n) _Pragma("unroll") for (int k = 0; k < 2; ++k) \
;         acc[ai][bj][m][n] = __builtin_amdgcn_mfma_f32_16x16x32_bf16(Bt[n][k], At[m][k], acc[ai][bj][m][n], 0, 0, 0); __builtin_amdgcn_s_setprio(0); } while (0)
; #define PG8_WAIT_V(n) asm volatile("s_waitcnt vmcnt(" #n ")" ::: "memory")
; #define PG8_WAIT_L(n) asm volatile("s_waitcnt lgkmcnt(" #n ")" ::: "memory")
; #define PG8_BAR __builtin_amdgcn_s_barrier()
; #define PG8_SCHED __builtin_amdgcn_sched_barrier(0)
; template <class Epi, class Sched, bool ALIGN_EPI = false, bool SP2 = false, bool MID = false>
; __device__ __forceinline__ void gemm_phase(PG8_LAS unsigned char* lds, const Gemm g, const Sched& S, const Epi& E, const PG8_LAS float* mid = nullptr) {
;     ...
;         for (int t = 0; t < nt; t += 2) {
;     ...
;             PG8_LDA(At, 1, 1); PG8_STAGE(PG8_SB(1, 0), b3, voffB); PG8_STAGE(PG8_SB(1, 1), b3 + hstepB, voffB); PG8_STAGE(PG8_SA(1, 0), a3, voffA);
;             PG8_WAIT_V(8); PG8_WAIT_L(0); PG8_BAR; PG8_MMA(1, 0, At, B0); PG8_MMA(1, 1, At, B1); PG8_BAR; PG8_SCHED;
	s_add_i32 s3, s3, s85
	v_lshl_add_u64 v[204:205], v[204:205], 0, s[16:17]
	s_mov_b32 m0, s3
	ds_read_b128 v[188:191], v221 offset:49152
	ds_read_b128 v[192:195], v221 offset:50176
	ds_read_b128 v[196:199], v221 offset:51200
	ds_read_b128 v[200:203], v221 offset:52224
	ds_read_b128 v[222:225], v221 offset:53248
	ds_read_b128 v[226:229], v221 offset:54272
	ds_read_b128 v[230:233], v221 offset:55296
	ds_read_b128 v[234:237], v221 offset:56320
	global_load_lds_dwordx4 v[204:205], off
	s_add_i32 m0, s3, 0x2000
	s_add_u32 s38, s38, 0x40080
	v_lshl_add_u64 v[204:205], v[210:211], 0, s[16:17]
	s_addc_u32 s39, s39, 0
	s_add_i32 s3, s71, s85
	global_load_lds_dwordx4 v[204:205], off
	v_lshl_add_u64 v[204:205], s[38:39], 0, v[176:177]
	s_mov_b32 m0, s3
	s_nop 0
	global_load_lds_dwordx4 v[204:205], off
	v_lshl_add_u64 v[204:205], s[38:39], 0, v[180:181]
	s_add_i32 m0, s3, 0x2000
	s_nop 0
	global_load_lds_dwordx4 v[204:205], off
	v_lshl_add_u64 v[204:205], v[212:213], 0, s[16:17]
	s_mov_b32 m0, s48
	s_nop 0
	global_load_lds_dwordx4 v[204:205], off
	v_lshl_add_u64 v[204:205], v[238:239], 0, s[16:17]
	s_mov_b32 m0, s49
	s_nop 0
	global_load_lds_dwordx4 v[204:205], off
	s_waitcnt vmcnt(8)
	s_waitcnt lgkmcnt(0)
	s_barrier
	s_waitcnt lgkmcnt(0)
	v_mfma_f32_16x16x32_bf16 v[60:63], v[130:133], v[188:191], v[60:63]
	v_mfma_f32_16x16x32_bf16 v[28:31], v[138:141], v[188:191], v[28:31]
	v_mfma_f32_16x16x32_bf16 v[52:55], v[130:133], v[196:199], v[52:55]
	v_mfma_f32_16x16x32_bf16 v[20:23], v[138:141], v[196:199], v[20:23]
	v_mfma_f32_16x16x32_bf16 v[44:47], v[130:133], v[222:225], v[44:47]
	v_mfma_f32_16x16x32_bf16 v[12:15], v[138:141], v[222:225], v[12:15]
	v_mfma_f32_16x16x32_bf16 v[36:39], v[130:133], v[230:233], v[36:39]
	v_mfma_f32_16x16x32_bf16 v[4:7], v[138:141], v[230:233], v[4:7]
	v_mfma_f32_16x16x32_bf16 v[60:63], v[134:137], v[192:195], v[60:63]
	v_mfma_f32_16x16x32_bf16 v[28:31], v[142:145], v[192:195], v[28:31]
	v_mfma_f32_16x16x32_bf16 v[52:55], v[134:137], v[200:203], v[52:55]
	v_mfma_f32_16x16x32_bf16 v[20:23], v[142:145], v[200:203], v[20:23]
	v_mfma_f32_16x16x32_bf16 v[44:47], v[134:137], v[226:229], v[44:47]
	v_mfma_f32_16x16x32_bf16 v[12:15], v[142:145], v[226:229], v[12:15]
	v_mfma_f32_16x16x32_bf16 v[36:39], v[134:137], v[234:237], v[36:39]
	v_mfma_f32_16x16x32_bf16 v[4:7], v[142:145], v[234:237], v[4:7]
	v_mfma_f32_16x16x32_bf16 v[56:59], v[146:149], v[188:191], v[56:59]
	v_mfma_f32_16x16x32_bf16 v[24:27], v[154:157], v[188:191], v[24:27]
	v_mfma_f32_16x16x32_bf16 v[48:51], v[146:149], v[196:199], v[48:51]
	v_mfma_f32_16x16x32_bf16 v[16:19], v[154:157], v[196:199], v[16:19]
	v_mfma_f32_16x16x32_bf16 v[40:43], v[146:149], v[222:225], v[40:43]
	v_mfma_f32_16x16x32_bf16 v[8:11], v[154:157], v[222:225], v[8:11]
	v_mfma_f32_16x16x32_bf16 v[32:35], v[146:149], v[230:233], v[32:35]
	v_mfma_f32_16x16x32_bf16 v[0:3], v[154:157], v[230:233], v[0:3]
	v_mfma_f32_16x16x32_bf16 v[56:59], v[150:153], v[192:195], v[56:59]
	v_mfma_f32_16x16x32_bf16 v[24:27], v[158:161], v[192:195], v[24:27]
	v_mfma_f32_16x16x32_bf16 v[48:51], v[150:153], v[200:203], v[48:51]
	v_mfma_f32_16x16x32_bf16 v[16:19], v[158:161], v[200:203], v[16:19]
	v_mfma_f32_16x16x32_bf16 v[40:43], v[150:153], v[226:229], v[40:43]
	v_mfma_f32_16x16x32_bf16 v[8:11], v[158:161], v[226:229], v[8:11]
	v_mfma_f32_16x16x32_bf16 v[32:35], v[150:153], v[234:237], v[32:35]
	v_mfma_f32_16x16x32_bf16 v[0:3], v[158:161], v[234:237], v[0:3]
	s_barrier
	s_add_i32 s70, s70, 2
	s_add_u32 s12, s12, 0x100
	s_addc_u32 s13, s13, 0
	s_add_u32 s63, s63, 0x100
	s_addc_u32 s65, s65, 0
	s_cmp_gt_u32 s70, 13
	s_cbranch_scc0 .LBB0_559
	v_readlane_b32 s12, v255, 47
	v_readlane_b32 s13, v255, 48
	s_and_b64 vcc, exec, s[12:13]
	s_cbranch_vccz .LBB0_562
	s_barrier

; #define PG8_STAGE(bufoff, gbase, voff) do { _Pragma("unroll") for (int _i = 0; _i < 2; ++_i) \
;         __builtin_amdgcn_global_load_lds((const unsigned*)((const char*)(gbase) + (voff)[_i]), (PG8_LAS unsigned*)(lds + (bufoff) + ldsw + _i * 8192), 16, 0, 0); } while (0)
; #define PG8_LDA(dst, b, h) do { _Pragma("unroll") for (int m = 0; m < 4; ++m) _Pragma("unroll") for (int k = 0; k < 2; ++k) dst[m][k] = *(const PG8_LAS bf16x8*)(lds + PG8_SA(b, h) + aoff + m * 2048 + k * 1024); } while (0)
; #define PG8_LDB(dst, b, h) do { _Pragma("unroll") for (int n = 0; n < 2; ++n) _Pragma("unroll") for (int k = 0; k < 2; ++k) dst[n][k] = *(const PG8_LAS bf16x8*)(lds + PG8_SB(b, h) + boff + n * 2048 + k * 1024); } while (0)
; #define PG8_MMA(ai, bj, At, Bt) do { __builtin_amdgcn_s_setprio(1); _Pragma("unroll") for (int m = 0; m < 4; ++m) _Pragma("unroll") for (int n = 0; n < 2; ++n) _Pragma("unroll") for (int k = 0; k < 2; ++k) \
;         acc[ai][bj][m][n] = __builtin_amdgcn_mfma_f32_16x16x32_bf16(Bt[n][k], At[m][k], acc[ai][bj][m][n], 0, 0, 0); __builtin_amdgcn_s_setprio(0); } while (0)
; #define PG8_WAIT_V(n) asm volatile("s_waitcnt vmcnt(" #n ")" ::: "memory")
; #define PG8_WAIT_L(n) asm volatile("s_waitcnt lgkmcnt(" #n ")" ::: "memory")
; #define PG8_BAR __builtin_amdgcn_s_barrier()
; #define PG8_SCHED __builtin_amdgcn_sched_barrier(0)
; template <class Epi, class Sched, bool ALIGN_EPI = false, bool SP2 = false, bool MID = false>
; __device__ __forceinline__ void gemm_phase(PG8_LAS unsigned char* lds, const Gemm g, const Sched& S, const Epi& E, const PG8_LAS float* mid = nullptr) {
;     ...
;             if constexpr (SP2) {
;             PG8_LDB(B0, 0, 0); PG8_LDB(B1, 0, 1); PG8_SCHED; PG8_LDA(At, 0, 0); PG8_STAGE(PG8_SA(1, 1), a1 + hstepA, voffA);
;             PG8_WAIT_V(8); PG8_WAIT_L(0); PG8_BAR; PG8_MMA(0, 0, At, B0); PG8_MMA(0, 1, At, B1); PG8_BAR; PG8_SCHED;
;             PG8_LDA(At, 0, 1); PG8_STAGE(PG8_SB(0, 0), b2, voffB); PG8_STAGE(PG8_SB(0, 1), b2 + hstepB, voffB); PG8_STAGE(PG8_SA(0, 0), a2, voffA);
.LBB0_705:
	s_add_u32 s12, s4, 0x100
	s_addc_u32 s13, s5, 0
	s_add_i32 s3, 0, 0x10000
	s_cmp_eq_u32 s69, 40
	s_cselect_b32 s47, s39, s13
	s_cselect_b32 s46, s38, s12
	s_cselect_b32 s21, s45, s68
	s_cselect_b32 s20, s44, s67
	s_add_i32 s70, 0, 0x14000
	v_add_u32_e32 v60, s3, v193
	v_add_u32_e32 v160, s70, v193
	ds_read_b128 v[48:51], v60
	ds_read_b128 v[52:55], v60 offset:1024
	ds_read_b128 v[56:59], v60 offset:2048
	ds_read_b128 v[60:63], v60 offset:3072
	ds_read_b128 v[156:159], v160
	ds_read_b128 v[174:177], v160 offset:1024
	ds_read_b128 v[178:181], v160 offset:2048
	ds_read_b128 v[182:185], v160 offset:3072
	v_lshl_add_u64 v[160:161], s[4:5], 0, v[154:155]
	s_add_i32 m0, s53, 0xc000
	ds_read_b128 v[186:189], v195
	ds_read_b128 v[196:199], v195 offset:1024
	ds_read_b128 v[200:203], v195 offset:2048
	ds_read_b128 v[220:223], v195 offset:3072
	ds_read_b128 v[224:227], v195 offset:4096
	ds_read_b128 v[228:231], v195 offset:5120
	ds_read_b128 v[232:235], v195 offset:6144
	ds_read_b128 v[236:239], v195 offset:7168
	global_load_lds_dwordx4 v[160:161], off
	v_lshl_add_u64 v[160:161], s[4:5], 0, v[152:153]
	s_add_i32 m0, s53, 0xe000
	s_nop 0
	global_load_lds_dwordx4 v[160:161], off
	s_waitcnt vmcnt(8)
	s_waitcnt lgkmcnt(0)
	s_barrier
	s_waitcnt lgkmcnt(0)
	v_mfma_f32_16x16x32_bf16 v[142:145], v[48:51], v[186:189], v[142:145]
	v_mfma_f32_16x16x32_bf16 v[138:141], v[56:59], v[186:189], v[138:141]
	v_mfma_f32_16x16x32_bf16 v[126:129], v[48:51], v[200:203], v[126:129]
	v_mfma_f32_16x16x32_bf16 v[122:125], v[56:59], v[200:203], v[122:125]
	v_mfma_f32_16x16x32_bf16 v[110:113], v[48:51], v[224:227], v[110:113]
	v_mfma_f32_16x16x32_bf16 v[106:109], v[56:59], v[224:227], v[106:109]
	v_mfma_f32_16x16x32_bf16 v[94:97], v[48:51], v[232:235], v[94:97]
	v_mfma_f32_16x16x32_bf16 v[90:93], v[56:59], v[232:235], v[90:93]
	v_mfma_f32_16x16x32_bf16 v[142:145], v[52:55], v[196:199], v[142:145]
	v_mfma_f32_16x16x32_bf16 v[138:141], v[60:63], v[196:199], v[138:141]
	v_mfma_f32_16x16x32_bf16 v[126:129], v[52:55], v[220:223], v[126:129]
	v_mfma_f32_16x16x32_bf16 v[122:125], v[60:63], v[220:223], v[122:125]
	v_mfma_f32_16x16x32_bf16 v[110:113], v[52:55], v[228:231], v[110:113]
	v_mfma_f32_16x16x32_bf16 v[106:109], v[60:63], v[228:231], v[106:109]
	v_mfma_f32_16x16x32_bf16 v[94:97], v[52:55], v[236:239], v[94:97]
	v_mfma_f32_16x16x32_bf16 v[90:93], v[60:63], v[236:239], v[90:93]
	v_mfma_f32_16x16x32_bf16 v[134:137], v[156:159], v[186:189], v[134:137]
	v_mfma_f32_16x16x32_bf16 v[130:133], v[178:181], v[186:189], v[130:133]
	v_mfma_f32_16x16x32_bf16 v[118:121], v[156:159], v[200:203], v[118:121]
	v_mfma_f32_16x16x32_bf16 v[114:117], v[178:181], v[200:203], v[114:117]
	v_mfma_f32_16x16x32_bf16 v[102:105], v[156:159], v[224:227], v[102:105]
	v_mfma_f32_16x16x32_bf16 v[98:101], v[178:181], v[224:227], v[98:101]
	v_mfma_f32_16x16x32_bf16 v[86:89], v[156:159], v[232:235], v[86:89]
	v_mfma_f32_16x16x32_bf16 v[82:85], v[178:181], v[232:235], v[82:85]
	v_mfma_f32_16x16x32_bf16 v[134:137], v[174:177], v[196:199], v[134:137]
	v_mfma_f32_16x16x32_bf16 v[130:133], v[182:185], v[196:199], v[130:133]
	v_mfma_f32_16x16x32_bf16 v[118:121], v[174:177], v[220:223], v[118:121]
	v_mfma_f32_16x16x32_bf16 v[114:117], v[182:185], v[220:223], v[114:117]
	v_mfma_f32_16x16x32_bf16 v[102:105], v[174:177], v[228:231], v[102:105]
	v_mfma_f32_16x16x32_bf16 v[98:101], v[182:185], v[228:231], v[98:101]
	v_mfma_f32_16x16x32_bf16 v[86:89], v[174:177], v[236:239], v[86:89]
	v_mfma_f32_16x16x32_bf16 v[82:85], v[182:185], v[236:239], v[82:85]
	s_barrier
	s_add_i32 s3, s3, s52
	v_lshl_add_u64 v[160:161], s[20:21], 0, v[80:81]
	s_mov_b32 m0, s3
	ds_read_b128 v[186:189], v195 offset:16384
	ds_read_b128 v[196:199], v195 offset:17408
	ds_read_b128 v[200:203], v195 offset:18432
	ds_read_b128 v[220:223], v195 offset:19456
	ds_read_b128 v[224:227], v195 offset:20480
	ds_read_b128 v[228:231], v195 offset:21504
	ds_read_b128 v[232:235], v195 offset:22528
	ds_read_b128 v[236:239], v195 offset:23552
	global_load_lds_dwordx4 v[160:161], off
	s_add_i32 m0, s3, 0x2000
	s_add_u32 s4, s20, 0xb0000
	v_lshl_add_u64 v[190:191], s[20:21], 0, v[150:151]
	s_addc_u32 s5, s21, 0
	s_add_i32 s3, s70, s52
	global_load_lds_dwordx4 v[190:191], off
	v_lshl_add_u64 v[204:205], s[4:5], 0, v[80:81]
	s_mov_b32 m0, s3
	v_lshl_add_u64 v[210:211], s[46:47], 0, v[148:149]
	global_load_lds_dwordx4 v[204:205], off
	v_lshl_add_u64 v[204:205], s[4:5], 0, v[150:151]
	s_add_i32 m0, s3, 0x2000
	s_nop 0
	global_load_lds_dwordx4 v[204:205], off
	v_lshl_add_u64 v[204:205], s[46:47], 0, v[146:147]
	s_mov_b32 m0, s53
	s_nop 0
	global_load_lds_dwordx4 v[204:205], off
	s_mov_b32 m0, s54
	s_nop 0
	global_load_lds_dwordx4 v[210:211], off
	s_waitcnt vmcnt(8)
	s_waitcnt lgkmcnt(0)
	s_barrier
; #define PG8_STAGE(bufoff, gbase, voff) do { _Pragma("unroll") for (int _i = 0; _i < 2; ++_i) \
;         __builtin_amdgcn_global_load_lds((const unsigned*)((const char*)(gbase) + (voff)[_i]), (PG8_LAS unsigned*)(lds + (bufoff) + ldsw + _i * 8192), 16, 0, 0); } while (0)
; #define PG8_LDA(dst, b, h) do { _Pragma("unroll") for (int m = 0; m < 4; ++m) _Pragma("unroll") for (int k = 0; k < 2; ++k) dst[m][k] = *(const PG8_LAS bf16x8*)(lds + PG8_SA(b, h) + aoff + m * 2048 + k * 1024); } while (0)
; #define PG8_LDB(dst, b, h) do { _Pragma("unroll") for (int n = 0; n < 2; ++n) _Pragma("unroll") for (int k = 0; k < 2; ++k) dst[n][k] = *(const PG8_LAS bf16x8*)(lds + PG8_SB(b, h) + boff + n * 2048 + k * 1024); } while (0)
; #define PG8_MMA(ai, bj, At, Bt) do { __builtin_amdgcn_s_setprio(1); _Pragma("unroll") for (int m = 0; m < 4; ++m) _Pragma("unroll") for (int n = 0; n < 2; ++n) _Pragma("unroll") for (int k = 0; k < 2; ++k) \
;         acc[ai][bj][m][n] = __builtin_amdgcn_mfma_f32_16x16x32_bf16(Bt[n][k], At[m][k], acc[ai][bj][m][n], 0, 0, 0); __builtin_amdgcn_s_setprio(0); } while (0)
; #define PG8_WAIT_V(n) asm volatile("s_waitcnt vmcnt(" #n ")" ::: "memory")
; #define PG8_WAIT_L(n) asm volatile("s_waitcnt lgkmcnt(" #n ")" ::: "memory")
; #define PG8_BAR __builtin_amdgcn_s_barrier()
; #define PG8_SCHED __builtin_amdgcn_sched_barrier(0)
; template <class Epi, class Sched, bool ALIGN_EPI = false, bool SP2 = false, bool MID = false>
; __device__ __forceinline__ void gemm_phase(PG8_LAS unsigned char* lds, const Gemm g, const Sched& S, const Epi& E, const PG8_LAS float* mid = nullptr) {
;     ...
;             PG8_WAIT_V(8); PG8_WAIT_L(0); PG8_BAR; PG8_MMA(1, 0, At, B0); PG8_MMA(1, 1, At, B1); PG8_BAR; PG8_SCHED;
;             PG8_LDB(B0, 1, 0); PG8_LDB(B1, 1, 1); PG8_SCHED; PG8_LDA(At, 1, 0); PG8_STAGE(PG8_SA(0, 1), a2 + hstepA, voffA);
;             PG8_WAIT_V(8); PG8_WAIT_L(0); PG8_BAR; PG8_MMA(0, 0, At, B0); PG8_MMA(0, 1, At, B1); PG8_BAR; PG8_SCHED;
	s_waitcnt lgkmcnt(0)
	v_mfma_f32_16x16x32_bf16 v[76:79], v[48:51], v[186:189], v[76:79]
	v_mfma_f32_16x16x32_bf16 v[72:75], v[56:59], v[186:189], v[72:75]
	v_mfma_f32_16x16x32_bf16 v[44:47], v[48:51], v[200:203], v[44:47]
	v_mfma_f32_16x16x32_bf16 v[40:43], v[56:59], v[200:203], v[40:43]
	v_mfma_f32_16x16x32_bf16 v[28:31], v[48:51], v[224:227], v[28:31]
	v_mfma_f32_16x16x32_bf16 v[24:27], v[56:59], v[224:227], v[24:27]
	v_mfma_f32_16x16x32_bf16 v[12:15], v[48:51], v[232:235], v[12:15]
	v_mfma_f32_16x16x32_bf16 v[8:11], v[56:59], v[232:235], v[8:11]
	v_mfma_f32_16x16x32_bf16 v[76:79], v[52:55], v[196:199], v[76:79]
	v_mfma_f32_16x16x32_bf16 v[72:75], v[60:63], v[196:199], v[72:75]
	v_mfma_f32_16x16x32_bf16 v[44:47], v[52:55], v[220:223], v[44:47]
	v_mfma_f32_16x16x32_bf16 v[40:43], v[60:63], v[220:223], v[40:43]
	v_mfma_f32_16x16x32_bf16 v[28:31], v[52:55], v[228:231], v[28:31]
	v_mfma_f32_16x16x32_bf16 v[24:27], v[60:63], v[228:231], v[24:27]
	v_mfma_f32_16x16x32_bf16 v[12:15], v[52:55], v[236:239], v[12:15]
	v_mfma_f32_16x16x32_bf16 v[8:11], v[60:63], v[236:239], v[8:11]
	v_mfma_f32_16x16x32_bf16 v[36:39], v[156:159], v[200:203], v[36:39]
	v_mfma_f32_16x16x32_bf16 v[32:35], v[178:181], v[200:203], v[32:35]
	v_mfma_f32_16x16x32_bf16 v[20:23], v[156:159], v[224:227], v[20:23]
	v_mfma_f32_16x16x32_bf16 v[16:19], v[178:181], v[224:227], v[16:19]
	v_mfma_f32_16x16x32_bf16 v[4:7], v[156:159], v[232:235], v[4:7]
	v_mfma_f32_16x16x32_bf16 v[0:3], v[178:181], v[232:235], v[0:3]
	v_mfma_f32_16x16x32_bf16 v[48:51], v[156:159], v[186:189], v[68:71]
	v_mfma_f32_16x16x32_bf16 v[52:55], v[178:181], v[186:189], v[64:67]
	v_mfma_f32_16x16x32_bf16 v[36:39], v[174:177], v[220:223], v[36:39]
	v_mfma_f32_16x16x32_bf16 v[32:35], v[182:185], v[220:223], v[32:35]
	v_mfma_f32_16x16x32_bf16 v[20:23], v[174:177], v[228:231], v[20:23]
	v_mfma_f32_16x16x32_bf16 v[16:19], v[182:185], v[228:231], v[16:19]
	v_mfma_f32_16x16x32_bf16 v[4:7], v[174:177], v[236:239], v[4:7]
	v_mfma_f32_16x16x32_bf16 v[0:3], v[182:185], v[236:239], v[0:3]
	v_mfma_f32_16x16x32_bf16 v[48:51], v[174:177], v[196:199], v[48:51]
	v_mfma_f32_16x16x32_bf16 v[52:55], v[182:185], v[196:199], v[52:55]
	s_barrier
	s_add_i32 s3, 0, 0x18000
	s_add_i32 s70, 0, 0x1c000
	v_add_u32_e32 v68, s3, v193
	v_add_u32_e32 v182, s70, v193
	ds_read_b128 v[56:59], v68
	ds_read_b128 v[60:63], v68 offset:1024
	ds_read_b128 v[64:67], v68 offset:2048
	ds_read_b128 v[68:71], v68 offset:3072
	ds_read_b128 v[156:159], v182
	ds_read_b128 v[174:177], v182 offset:1024
	ds_read_b128 v[178:181], v182 offset:2048
	ds_read_b128 v[182:185], v182 offset:3072
	s_add_u32 s4, s46, 0xb0000
	s_addc_u32 s5, s47, 0
	s_mov_b32 m0, s55
	v_lshl_add_u64 v[212:213], s[4:5], 0, v[146:147]
	ds_read_b128 v[186:189], v195 offset:32768
	ds_read_b128 v[196:199], v195 offset:33792
	ds_read_b128 v[200:203], v195 offset:34816
	ds_read_b128 v[220:223], v195 offset:35840
	ds_read_b128 v[224:227], v195 offset:36864
	ds_read_b128 v[228:231], v195 offset:37888
	ds_read_b128 v[232:235], v195 offset:38912
	ds_read_b128 v[236:239], v195 offset:39936
	global_load_lds_dwordx4 v[212:213], off
	v_lshl_add_u64 v[212:213], s[4:5], 0, v[148:149]
	s_mov_b32 m0, s56
	s_nop 0
	global_load_lds_dwordx4 v[212:213], off
	s_waitcnt vmcnt(8)
	s_waitcnt lgkmcnt(0)
	s_barrier
	s_waitcnt lgkmcnt(0)
	v_mfma_f32_16x16x32_bf16 v[142:145], v[56:59], v[186:189], v[142:145]
	v_mfma_f32_16x16x32_bf16 v[138:141], v[64:67], v[186:189], v[138:141]
	v_mfma_f32_16x16x32_bf16 v[126:129], v[56:59], v[200:203], v[126:129]
	v_mfma_f32_16x16x32_bf16 v[122:125], v[64:67], v[200:203], v[122:125]
	v_mfma_f32_16x16x32_bf16 v[110:113], v[56:59], v[224:227], v[110:113]
	v_mfma_f32_16x16x32_bf16 v[106:109], v[64:67], v[224:227], v[106:109]
	v_mfma_f32_16x16x32_bf16 v[94:97], v[56:59], v[232:235], v[94:97]
	v_mfma_f32_16x16x32_bf16 v[90:93], v[64:67], v[232:235], v[90:93]
	v_mfma_f32_16x16x32_bf16 v[142:145], v[60:63], v[196:199], v[142:145]
	v_mfma_f32_16x16x32_bf16 v[138:141], v[68:71], v[196:199], v[138:141]
	v_mfma_f32_16x16x32_bf16 v[126:129], v[60:63], v[220:223], v[126:129]
	v_mfma_f32_16x16x32_bf16 v[122:125], v[68:71], v[220:223], v[122:125]
	v_mfma_f32_16x16x32_bf16 v[110:113], v[60:63], v[228:231], v[110:113]
	v_mfma_f32_16x16x32_bf16 v[106:109], v[68:71], v[228:231], v[106:109]
	v_mfma_f32_16x16x32_bf16 v[94:97], v[60:63], v[236:239], v[94:97]
	v_mfma_f32_16x16x32_bf16 v[90:93], v[68:71], v[236:239], v[90:93]
	v_mfma_f32_16x16x32_bf16 v[134:137], v[156:159], v[186:189], v[134:137]
	v_mfma_f32_16x16x32_bf16 v[130:133], v[178:181], v[186:189], v[130:133]
	v_mfma_f32_16x16x32_bf16 v[118:121], v[156:159], v[200:203], v[118:121]
	v_mfma_f32_16x16x32_bf16 v[114:117], v[178:181], v[200:203], v[114:117]
	v_mfma_f32_16x16x32_bf16 v[102:105], v[156:159], v[224:227], v[102:105]
	v_mfma_f32_16x16x32_bf16 v[98:101], v[178:181], v[224:227], v[98:101]
	v_mfma_f32_16x16x32_bf16 v[86:89], v[156:159], v[232:235], v[86:89]
	v_mfma_f32_16x16x32_bf16 v[82:85], v[178:181], v[232:235], v[82:85]
	v_mfma_f32_16x16x32_bf16 v[134:137], v[174:177], v[196:199], v[134:137]
	v_mfma_f32_16x16x32_bf16 v[130:133], v[182:185], v[196:199], v[130:133]
	v_mfma_f32_16x16x32_bf16 v[118:121], v[174:177], v[220:223], v[118:121]
	v_mfma_f32_16x16x32_bf16 v[114:117], v[182:185], v[220:223], v[114:117]
	v_mfma_f32_16x16x32_bf16 v[102:105], v[174:177], v[228:231], v[102:105]
	v_mfma_f32_16x16x32_bf16 v[98:101], v[182:185], v[228:231], v[98:101]
	v_mfma_f32_16x16x32_bf16 v[86:89], v[174:177], v[236:239], v[86:89]
	v_mfma_f32_16x16x32_bf16 v[82:85], v[182:185], v[236:239], v[82:85]
	s_barrier
; #define PG8_STAGE(bufoff, gbase, voff) do { _Pragma("unroll") for (int _i = 0; _i < 2; ++_i) \
;         __builtin_amdgcn_global_load_lds((const unsigned*)((const char*)(gbase) + (voff)[_i]), (PG8_LAS unsigned*)(lds + (bufoff) + ldsw + _i * 8192), 16, 0, 0); } while (0)
; #define PG8_LDA(dst, b, h) do { _Pragma("unroll") for (int m = 0; m < 4; ++m) _Pragma("unroll") for (int k = 0; k < 2; ++k) dst[m][k] = *(const PG8_LAS bf16x8*)(lds + PG8_SA(b, h) + aoff + m * 2048 + k * 1024); } while (0)
; #define PG8_MMA(ai, bj, At, Bt) do { __builtin_amdgcn_s_setprio(1); _Pragma("unroll") for (int m = 0; m < 4; ++m) _Pragma("unroll") for (int n = 0; n < 2; ++n) _Pragma("unroll") for (int k = 0; k < 2; ++k) \
;         acc[ai][bj][m][n] = __builtin_amdgcn_mfma_f32_16x16x32_bf16(Bt[n][k], At[m][k], acc[ai][bj][m][n], 0, 0, 0); __builtin_amdgcn_s_setprio(0); } while (0)
; #define PG8_WAIT_V(n) asm volatile("s_waitcnt vmcnt(" #n ")" ::: "memory")
; #define PG8_WAIT_L(n) asm volatile("s_waitcnt lgkmcnt(" #n ")" ::: "memory")
; #define PG8_BAR __builtin_amdgcn_s_barrier()
; #define PG8_SCHED __builtin_amdgcn_sched_barrier(0)
; template <class Epi, class Sched, bool ALIGN_EPI = false, bool SP2 = false, bool MID = false>
; __device__ __forceinline__ void gemm_phase(PG8_LAS unsigned char* lds, const Gemm g, const Sched& S, const Epi& E, const PG8_LAS float* mid = nullptr) {
;     ...
;         for (int t = 0; t < nt; t += 2) {
;     ...
;             PG8_LDA(At, 1, 1); PG8_STAGE(PG8_SB(1, 0), b3, voffB); PG8_STAGE(PG8_SB(1, 1), b3 + hstepB, voffB); PG8_STAGE(PG8_SA(1, 0), a3, voffA);
;             PG8_WAIT_V(8); PG8_WAIT_L(0); PG8_BAR; PG8_MMA(1, 0, At, B0); PG8_MMA(1, 1, At, B1); PG8_BAR; PG8_SCHED;
	s_add_i32 s3, s3, s52
	v_lshl_add_u64 v[160:161], v[160:161], 0, s[16:17]
	s_mov_b32 m0, s3
	ds_read_b128 v[186:189], v195 offset:49152
	ds_read_b128 v[196:199], v195 offset:50176
	ds_read_b128 v[200:203], v195 offset:51200
	ds_read_b128 v[220:223], v195 offset:52224
	ds_read_b128 v[224:227], v195 offset:53248
	ds_read_b128 v[228:231], v195 offset:54272
	ds_read_b128 v[232:235], v195 offset:55296
	ds_read_b128 v[236:239], v195 offset:56320
	global_load_lds_dwordx4 v[160:161], off
	s_add_i32 m0, s3, 0x2000
	s_add_u32 s4, s20, 0xb0080
	v_lshl_add_u64 v[160:161], v[190:191], 0, s[16:17]
	s_addc_u32 s5, s21, 0
	s_add_i32 s3, s70, s52
	global_load_lds_dwordx4 v[160:161], off
	v_lshl_add_u64 v[160:161], s[4:5], 0, v[80:81]
	s_mov_b32 m0, s3
	s_nop 0
	global_load_lds_dwordx4 v[160:161], off
	v_lshl_add_u64 v[160:161], s[4:5], 0, v[150:151]
	s_add_i32 m0, s3, 0x2000
	s_nop 0
	global_load_lds_dwordx4 v[160:161], off
	v_lshl_add_u64 v[160:161], v[204:205], 0, s[16:17]
	s_mov_b32 m0, s59
	s_nop 0
	global_load_lds_dwordx4 v[160:161], off
	v_lshl_add_u64 v[160:161], v[210:211], 0, s[16:17]
	s_mov_b32 m0, s60
	s_nop 0
	global_load_lds_dwordx4 v[160:161], off
	s_waitcnt vmcnt(8)
	s_waitcnt lgkmcnt(0)
	s_barrier
	s_waitcnt lgkmcnt(0)
	v_mfma_f32_16x16x32_bf16 v[76:79], v[56:59], v[186:189], v[76:79]
	v_mfma_f32_16x16x32_bf16 v[72:75], v[64:67], v[186:189], v[72:75]
	v_mfma_f32_16x16x32_bf16 v[44:47], v[56:59], v[200:203], v[44:47]
	v_mfma_f32_16x16x32_bf16 v[40:43], v[64:67], v[200:203], v[40:43]
	v_mfma_f32_16x16x32_bf16 v[28:31], v[56:59], v[224:227], v[28:31]
	v_mfma_f32_16x16x32_bf16 v[24:27], v[64:67], v[224:227], v[24:27]
	v_mfma_f32_16x16x32_bf16 v[12:15], v[56:59], v[232:235], v[12:15]
	v_mfma_f32_16x16x32_bf16 v[8:11], v[64:67], v[232:235], v[8:11]
	v_mfma_f32_16x16x32_bf16 v[76:79], v[60:63], v[196:199], v[76:79]
	v_mfma_f32_16x16x32_bf16 v[72:75], v[68:71], v[196:199], v[72:75]
	v_mfma_f32_16x16x32_bf16 v[44:47], v[60:63], v[220:223], v[44:47]
	v_mfma_f32_16x16x32_bf16 v[40:43], v[68:71], v[220:223], v[40:43]
	v_mfma_f32_16x16x32_bf16 v[28:31], v[60:63], v[228:231], v[28:31]
	v_mfma_f32_16x16x32_bf16 v[24:27], v[68:71], v[228:231], v[24:27]
	v_mfma_f32_16x16x32_bf16 v[12:15], v[60:63], v[236:239], v[12:15]
	v_mfma_f32_16x16x32_bf16 v[8:11], v[68:71], v[236:239], v[8:11]
	v_mfma_f32_16x16x32_bf16 v[48:51], v[156:159], v[186:189], v[48:51]
	v_mfma_f32_16x16x32_bf16 v[68:71], v[174:177], v[196:199], v[48:51]
	v_mfma_f32_16x16x32_bf16 v[48:51], v[178:181], v[186:189], v[52:55]
	v_mfma_f32_16x16x32_bf16 v[36:39], v[156:159], v[200:203], v[36:39]
	v_mfma_f32_16x16x32_bf16 v[32:35], v[178:181], v[200:203], v[32:35]
	v_mfma_f32_16x16x32_bf16 v[20:23], v[156:159], v[224:227], v[20:23]
	v_mfma_f32_16x16x32_bf16 v[16:19], v[178:181], v[224:227], v[16:19]
	v_mfma_f32_16x16x32_bf16 v[4:7], v[156:159], v[232:235], v[4:7]
	v_mfma_f32_16x16x32_bf16 v[0:3], v[178:181], v[232:235], v[0:3]
	v_mfma_f32_16x16x32_bf16 v[64:67], v[182:185], v[196:199], v[48:51]
	v_mfma_f32_16x16x32_bf16 v[36:39], v[174:177], v[220:223], v[36:39]
	v_mfma_f32_16x16x32_bf16 v[32:35], v[182:185], v[220:223], v[32:35]
	v_mfma_f32_16x16x32_bf16 v[20:23], v[174:177], v[228:231], v[20:23]
	v_mfma_f32_16x16x32_bf16 v[16:19], v[182:185], v[228:231], v[16:19]
	v_mfma_f32_16x16x32_bf16 v[4:7], v[174:177], v[236:239], v[4:7]
	v_mfma_f32_16x16x32_bf16 v[0:3], v[182:185], v[236:239], v[0:3]
	s_barrier
	s_add_i32 s69, s69, 2
	s_add_u32 s67, s67, 0x100
	s_addc_u32 s68, s68, 0
	s_cmp_gt_u32 s69, 41
	s_mov_b64 s[4:5], s[12:13]
	s_cbranch_scc0 .LBB0_705
	s_and_b64 vcc, exec, s[42:43]
	s_cbranch_vccz .LBB0_708
	s_barrier
